# nontemporal stores for the plain-epilogue GEMM outputs (P, Y) to keep operand tiles in L2
# speedup vs baseline: 1.0152x; 1.0057x over previous
; #define LAS __attribute__((address_space(3)))
; DI f32x16 mfma32(bf16x8 a, bf16x8 b, f32x16 c) { return __builtin_amdgcn_mfma_f32_32x32x16_bf16(a, b, c, 0, 0, 0); }
;     ...
;   for (int kt = 0; kt < nk; ++kt) {
;     const int kn = (kt + 2 < nk) ? (kt + 2) : (nk - 1);
;     const LAS char* cur = lds + s0;
;     bf16x8 af[2][2], bfr[2][4];
; #pragma unroll
;     for (int kk = 0; kk < 2; ++kk) {
;       const int xo = kk ? x1 : x0;
;       af[kk][0] = *(const LAS bf16x8*)(cur + a_rd + xo);
;       bfr[kk][0] = *(const LAS bf16x8*)(cur + b_rd + xo);
;       bfr[kk][1] = *(const LAS bf16x8*)(cur + b_rd + 2048 + xo);
;       af[kk][1] = *(const LAS bf16x8*)(cur + a_rd + 2048 + xo);
;       bfr[kk][2] = *(const LAS bf16x8*)(cur + b_rd + 4096 + xo);
;       bfr[kk][3] = *(const LAS bf16x8*)(cur + b_rd + 6144 + xo);
;     }
;     DMA_STEP_(kn, s2);
; #pragma unroll
;     for (int kk = 0; kk < 2; ++kk) {
;       acc[0][0] = mfma32(bfr[kk][0], af[kk][0], acc[0][0]); acc[0][1] = mfma32(bfr[kk][1], af[kk][0], acc[0][1]);
;       acc[1][0] = mfma32(bfr[kk][0], af[kk][1], acc[1][0]); acc[1][1] = mfma32(bfr[kk][1], af[kk][1], acc[1][1]);
;       acc[0][2] = mfma32(bfr[kk][2], af[kk][0], acc[0][2]); acc[0][3] = mfma32(bfr[kk][3], af[kk][0], acc[0][3]);
;       acc[1][2] = mfma32(bfr[kk][2], af[kk][1], acc[1][2]); acc[1][3] = mfma32(bfr[kk][3], af[kk][1], acc[1][3]);
;     }
;     __builtin_amdgcn_sched_group_barrier(0x100, 12, 0);
;     __builtin_amdgcn_sched_group_barrier(0x010, 6, 0);
;     __builtin_amdgcn_sched_group_barrier(0x008, 16, 0);
;     asm volatile("s_waitcnt vmcnt(6) lgkmcnt(0)" ::: "memory");
;     __builtin_amdgcn_s_barrier();
;     asm volatile("" ::: "memory");
;     s0 = (s0 == 2 * STG) ? 0 : s0 + STG;
;     s2 = (s2 == 2 * STG) ? 0 : s2 + STG;
;   }
.LBB0_21:
	s_add_i32 s11, s42, 16
	s_mov_b32 s10, s40
	v_add_u32_e32 v142, s11, v219
	v_add_u32_e32 v150, s11, v218
	s_min_u32 s10, s10, 29
	v_add_u32_e32 v142, v142, v220
	v_add_u32_e32 v150, v150, v220
	s_lshl_b32 s70, s10, 6
	ds_read_b128 v[138:141], v142
	ds_read_b128 v[162:165], v150 offset:8192
	ds_read_b128 v[166:169], v150 offset:10240
	ds_read_b128 v[142:145], v142 offset:2048
	ds_read_b128 v[146:149], v150 offset:12288
	ds_read_b128 v[150:153], v150 offset:14336
	v_lshl_add_u64 v[222:223], v[192:193], 0, s[70:71]
	s_add_i32 s10, s13, s41
	v_lshl_add_u64 v[224:225], v[222:223], 0, s[24:25]
	s_mov_b32 m0, s10
	v_lshl_add_u64 v[222:223], v[222:223], 0, s[38:39]
	s_mul_i32 s100, s70, 0x400
	s_waitcnt lgkmcnt(6)
	v_mfma_f32_32x32x16_bf16 v[114:129], v[182:185], v[154:157], v[114:129]
	global_load_lds_dwordx4 v[224:225], off
	s_add_i32 m0, s10, 0x400
	v_mfma_f32_32x32x16_bf16 v[98:113], v[178:181], v[154:157], v[98:113]
	global_load_lds_dwordx4 v[222:223], off
	v_lshl_add_u64 v[224:225], v[194:195], 0, s[100:101]
	s_add_i32 s10, s29, s41
	s_add_i32 m0, s10, 0x2000
	v_mfma_f32_32x32x16_bf16 v[66:81], v[182:185], v[158:161], v[66:81]
	global_load_lds_dwordx4 v[224:225], off
	v_mfma_f32_32x32x16_bf16 v[34:49], v[178:181], v[158:161], v[34:49]
	global_load_lds_dwordx4 v[224:225], off offset:1024
	v_mfma_f32_32x32x16_bf16 v[82:97], v[174:177], v[154:157], v[82:97]
	global_load_lds_dwordx4 v[224:225], off offset:2048
	v_mfma_f32_32x32x16_bf16 v[50:65], v[170:173], v[154:157], v[50:65]
	global_load_lds_dwordx4 v[224:225], off offset:3072
	v_mfma_f32_32x32x16_bf16 v[18:33], v[174:177], v[158:161], v[18:33]
	s_add_i32 s10, s42, 0x6000
	s_cmpk_lg_u32 s42, 0xc000
	s_cselect_b32 s42, s10, 0
	s_add_i32 s10, s41, 0x6000
	s_cmpk_lg_u32 s41, 0xc000
	s_cselect_b32 s41, s10, 0
	v_mfma_f32_32x32x16_bf16 v[2:17], v[170:173], v[158:161], v[2:17]
	s_add_i32 s11, s42, 16
	s_waitcnt vmcnt(6) lgkmcnt(0)
	s_barrier
	v_add_u32_e32 v158, s11, v219
	v_add_u32_e32 v170, s11, v218
	v_add_u32_e32 v158, v158, v0
	v_add_u32_e32 v170, v170, v0
	ds_read_b128 v[154:157], v158
	ds_read_b128 v[182:185], v170 offset:8192
	ds_read_b128 v[178:181], v170 offset:10240
	ds_read_b128 v[158:161], v158 offset:2048
	ds_read_b128 v[174:177], v170 offset:12288
	ds_read_b128 v[170:173], v170 offset:14336
	v_mfma_f32_32x32x16_bf16 v[114:129], v[162:165], v[138:141], v[114:129]
	v_mfma_f32_32x32x16_bf16 v[98:113], v[166:169], v[138:141], v[98:113]
	v_mfma_f32_32x32x16_bf16 v[66:81], v[162:165], v[142:145], v[66:81]
	v_mfma_f32_32x32x16_bf16 v[34:49], v[166:169], v[142:145], v[34:49]
	v_mfma_f32_32x32x16_bf16 v[82:97], v[146:149], v[138:141], v[82:97]
	v_mfma_f32_32x32x16_bf16 v[50:65], v[150:153], v[138:141], v[50:65]
	v_mfma_f32_32x32x16_bf16 v[18:33], v[146:149], v[142:145], v[18:33]
	v_mfma_f32_32x32x16_bf16 v[2:17], v[150:153], v[142:145], v[2:17]
	s_add_i32 s11, s42, 16
	s_add_i32 s10, s40, 1
	v_add_u32_e32 v142, s11, v219
	v_add_u32_e32 v150, s11, v218
	s_min_u32 s10, s10, 29
	v_add_u32_e32 v142, v142, v220
	v_add_u32_e32 v150, v150, v220
	s_lshl_b32 s70, s10, 6
	ds_read_b128 v[138:141], v142
	ds_read_b128 v[162:165], v150 offset:8192
	ds_read_b128 v[166:169], v150 offset:10240
	ds_read_b128 v[142:145], v142 offset:2048
	ds_read_b128 v[146:149], v150 offset:12288
	ds_read_b128 v[150:153], v150 offset:14336
	v_lshl_add_u64 v[222:223], v[192:193], 0, s[70:71]
	s_add_i32 s10, s13, s41
	v_lshl_add_u64 v[224:225], v[222:223], 0, s[24:25]
	s_mov_b32 m0, s10
	v_lshl_add_u64 v[222:223], v[222:223], 0, s[38:39]
	s_mul_i32 s100, s70, 0x400
	s_waitcnt lgkmcnt(6)
	v_mfma_f32_32x32x16_bf16 v[114:129], v[182:185], v[154:157], v[114:129]
	global_load_lds_dwordx4 v[224:225], off
	s_add_i32 m0, s10, 0x400
	v_mfma_f32_32x32x16_bf16 v[98:113], v[178:181], v[154:157], v[98:113]
	global_load_lds_dwordx4 v[222:223], off
	v_lshl_add_u64 v[224:225], v[194:195], 0, s[100:101]
	s_add_i32 s10, s29, s41
	s_add_i32 m0, s10, 0x2000
	v_mfma_f32_32x32x16_bf16 v[66:81], v[182:185], v[158:161], v[66:81]
	global_load_lds_dwordx4 v[224:225], off
	v_mfma_f32_32x32x16_bf16 v[34:49], v[178:181], v[158:161], v[34:49]
	global_load_lds_dwordx4 v[224:225], off offset:1024
	v_mfma_f32_32x32x16_bf16 v[82:97], v[174:177], v[154:157], v[82:97]
	global_load_lds_dwordx4 v[224:225], off offset:2048
	v_mfma_f32_32x32x16_bf16 v[50:65], v[170:173], v[154:157], v[50:65]
	global_load_lds_dwordx4 v[224:225], off offset:3072
	v_mfma_f32_32x32x16_bf16 v[18:33], v[174:177], v[158:161], v[18:33]
	s_add_i32 s10, s42, 0x6000
	s_cmpk_lg_u32 s42, 0xc000
	s_cselect_b32 s42, s10, 0
	s_add_i32 s10, s41, 0x6000
	s_cmpk_lg_u32 s41, 0xc000
	s_cselect_b32 s41, s10, 0
	v_mfma_f32_32x32x16_bf16 v[2:17], v[170:173], v[158:161], v[2:17]
	s_add_i32 s11, s42, 16
	s_waitcnt vmcnt(6) lgkmcnt(0)
	s_barrier
	v_add_u32_e32 v158, s11, v219
	v_add_u32_e32 v170, s11, v218
	v_add_u32_e32 v158, v158, v0
	v_add_u32_e32 v170, v170, v0
	ds_read_b128 v[154:157], v158
	ds_read_b128 v[182:185], v170 offset:8192
	ds_read_b128 v[178:181], v170 offset:10240
	ds_read_b128 v[158:161], v158 offset:2048
	ds_read_b128 v[174:177], v170 offset:12288
	ds_read_b128 v[170:173], v170 offset:14336
	v_mfma_f32_32x32x16_bf16 v[114:129], v[162:165], v[138:141], v[114:129]
	v_mfma_f32_32x32x16_bf16 v[98:113], v[166:169], v[138:141], v[98:113]
	v_mfma_f32_32x32x16_bf16 v[66:81], v[162:165], v[142:145], v[66:81]
	v_mfma_f32_32x32x16_bf16 v[34:49], v[166:169], v[142:145], v[34:49]
	v_mfma_f32_32x32x16_bf16 v[82:97], v[146:149], v[138:141], v[82:97]
	v_mfma_f32_32x32x16_bf16 v[50:65], v[150:153], v[138:141], v[50:65]
	v_mfma_f32_32x32x16_bf16 v[18:33], v[146:149], v[142:145], v[18:33]
	v_mfma_f32_32x32x16_bf16 v[2:17], v[150:153], v[142:145], v[2:17]
	s_add_i32 s40, s40, 2
	s_cmp_lg_u32 s40, 32
	s_cbranch_scc1 .LBB0_21
; DI unsigned pk2(float a, float b) { f32x2 v = {a, b}; bf2_t r = __builtin_convertvector(v, bf2_t); return __builtin_bit_cast(unsigned, r); }
;     ...
;   asm volatile("s_waitcnt vmcnt(0)" ::: "memory");
;   __builtin_amdgcn_s_barrier();
;   asm volatile("" ::: "memory");
;     ...
;   {
;     const int h = lane >> 5, cl = lane & 31;
; #pragma unroll
;     for (int i = 0; i < 2; ++i)
; #pragma unroll
;       for (int j = 0; j < 4; ++j)
; #pragma unroll
;         for (int g = 0; g < 4; ++g) {
;           u32x2 w; w.x = pk2(acc[i][j][4 * g], acc[i][j][4 * g + 1]); w.y = pk2(acc[i][j][4 * g + 2], acc[i][j][4 * g + 3]);
;           *(u32x2*)(smem + (wr * 64 + i * 32 + cl) * 528 + (wc * 128 + j * 32 + 8 * g + 4 * h) * 2) = w;
;         }
;   }
;   __syncthreads();
	s_waitcnt lgkmcnt(0)
	s_setprio 0
	v_mul_lo_u32 v0, v197, s55
	v_add_u32_e32 v0, 16, v0
	s_nop 1
	v_cvt_pk_bf16_f32 v114, v114, v115
	v_cvt_pk_bf16_f32 v115, v116, v117
	v_lshlrev_b32_e32 v116, 3, v196
	s_lshl_b32 s10, s28, 1
	v_add3_u32 v0, v0, v116, s10
	v_cvt_pk_bf16_f32 v116, v118, v119
	v_cvt_pk_bf16_f32 v117, v120, v121
	v_cvt_pk_bf16_f32 v98, v98, v99
	v_cvt_pk_bf16_f32 v99, v100, v101
	v_cvt_pk_bf16_f32 v100, v102, v103
	v_cvt_pk_bf16_f32 v101, v104, v105
	v_cvt_pk_bf16_f32 v82, v82, v83
	v_cvt_pk_bf16_f32 v83, v84, v85
	v_cvt_pk_bf16_f32 v84, v86, v87
	v_cvt_pk_bf16_f32 v85, v88, v89
	v_cvt_pk_bf16_f32 v50, v50, v51
	v_cvt_pk_bf16_f32 v51, v52, v53
	v_cvt_pk_bf16_f32 v52, v54, v55
	v_cvt_pk_bf16_f32 v53, v56, v57
	s_waitcnt vmcnt(0)
	s_barrier
	ds_write2_b64 v0, v[114:115], v[116:117] offset1:2
	v_cvt_pk_bf16_f32 v114, v122, v123
	v_cvt_pk_bf16_f32 v115, v124, v125
	v_cvt_pk_bf16_f32 v116, v126, v127
	v_cvt_pk_bf16_f32 v117, v128, v129
	ds_write2_b64 v0, v[98:99], v[100:101] offset0:8 offset1:10
	v_cvt_pk_bf16_f32 v98, v106, v107
	v_cvt_pk_bf16_f32 v99, v108, v109
	v_cvt_pk_bf16_f32 v100, v110, v111
	v_cvt_pk_bf16_f32 v101, v112, v113
	ds_write2_b64 v0, v[82:83], v[84:85] offset0:16 offset1:18
	v_cvt_pk_bf16_f32 v82, v90, v91
	v_cvt_pk_bf16_f32 v83, v92, v93
	v_cvt_pk_bf16_f32 v84, v94, v95
	v_cvt_pk_bf16_f32 v85, v96, v97
	ds_write2_b64 v0, v[50:51], v[52:53] offset0:24 offset1:26
	v_cvt_pk_bf16_f32 v50, v58, v59
	v_cvt_pk_bf16_f32 v51, v60, v61
	v_cvt_pk_bf16_f32 v52, v62, v63
	v_cvt_pk_bf16_f32 v53, v64, v65
	ds_write2_b64 v0, v[114:115], v[116:117] offset0:4 offset1:6
	ds_write2_b64 v0, v[98:99], v[100:101] offset0:12 offset1:14
	ds_write2_b64 v0, v[82:83], v[84:85] offset0:20 offset1:22
	ds_write2_b64 v0, v[50:51], v[52:53] offset0:28 offset1:30
	v_cvt_pk_bf16_f32 v50, v66, v67
	v_cvt_pk_bf16_f32 v51, v68, v69
	v_cvt_pk_bf16_f32 v52, v70, v71
	v_cvt_pk_bf16_f32 v53, v72, v73
	v_add_u32_e32 v0, 0x4000, v0
	v_cvt_pk_bf16_f32 v34, v34, v35
	v_cvt_pk_bf16_f32 v35, v36, v37
	v_cvt_pk_bf16_f32 v36, v38, v39
	v_cvt_pk_bf16_f32 v37, v40, v41
	v_cvt_pk_bf16_f32 v18, v18, v19
	v_cvt_pk_bf16_f32 v19, v20, v21
	v_cvt_pk_bf16_f32 v20, v22, v23
	v_cvt_pk_bf16_f32 v21, v24, v25
	v_cvt_pk_bf16_f32 v2, v2, v3
	v_cvt_pk_bf16_f32 v3, v4, v5
	v_cvt_pk_bf16_f32 v4, v6, v7
	v_cvt_pk_bf16_f32 v5, v8, v9
	ds_write2_b64 v0, v[50:51], v[52:53] offset0:64 offset1:66
	v_cvt_pk_bf16_f32 v50, v74, v75
	v_cvt_pk_bf16_f32 v51, v76, v77
	v_cvt_pk_bf16_f32 v52, v78, v79
	v_cvt_pk_bf16_f32 v53, v80, v81
	ds_write2_b64 v0, v[34:35], v[36:37] offset0:72 offset1:74
	v_cvt_pk_bf16_f32 v34, v42, v43
	v_cvt_pk_bf16_f32 v35, v44, v45
	v_cvt_pk_bf16_f32 v36, v46, v47
	v_cvt_pk_bf16_f32 v37, v48, v49
	ds_write2_b64 v0, v[18:19], v[20:21] offset0:80 offset1:82
	v_cvt_pk_bf16_f32 v18, v26, v27
	v_cvt_pk_bf16_f32 v19, v28, v29
	v_cvt_pk_bf16_f32 v20, v30, v31
	v_cvt_pk_bf16_f32 v21, v32, v33
	ds_write2_b64 v0, v[2:3], v[4:5] offset0:88 offset1:90
	v_cvt_pk_bf16_f32 v2, v10, v11
	v_cvt_pk_bf16_f32 v3, v12, v13
	v_cvt_pk_bf16_f32 v4, v14, v15
	v_cvt_pk_bf16_f32 v5, v16, v17
	s_lshl_b64 s[14:15], s[14:15], 1
	ds_write2_b64 v0, v[50:51], v[52:53] offset0:68 offset1:70
	ds_write2_b64 v0, v[34:35], v[36:37] offset0:76 offset1:78
	ds_write2_b64 v0, v[18:19], v[20:21] offset0:84 offset1:86
	ds_write2_b64 v0, v[2:3], v[4:5] offset0:92 offset1:94
	s_waitcnt vmcnt(0) lgkmcnt(0)
	s_barrier
; #define GAS __attribute__((address_space(1)))
;     ...
;   int tid2 = tid; asm volatile("" : "+v"(tid2));
;   if (EPI == 0) {
; #pragma unroll
;     for (int i = 0; i < 16; ++i) {
;       const int id = tid2 + 256 * i, r = id >> 5, c8 = (id & 31) * 8;
;       const u32x4 v = *(const u32x4*)(smem + r * 528 + c8 * 2);
;       *(GAS u32x4*)(ea.out + (size_t)(m0 + r) * ea.ldo + n0 + c8) = v;
;     }
	s_add_u32 s14, s19, s14
	v_lshlrev_b32_e32 v0, 4, v189
	v_and_b32_e32 v0, 0x1f0, v0
	s_addc_u32 s15, s20, s15
	v_add_u32_e32 v10, 16, v0
	v_lshl_add_u64 v[12:13], s[14:15], 0, v[0:1]
	v_ashrrev_i32_e32 v0, 5, v189
	v_mad_u64_u32 v[2:3], s[14:15], v0, s55, v[10:11]
	ds_read_b128 v[2:5], v2
	v_add_u32_e32 v6, s12, v0
	v_ashrrev_i32_e32 v7, 31, v6
	v_add_u32_e32 v0, 0x100, v189
	v_lshlrev_b64 v[6:7], 11, v[6:7]
	v_ashrrev_i32_e32 v0, 5, v0
	v_lshl_add_u64 v[14:15], v[12:13], 0, v[6:7]
	v_mad_u64_u32 v[6:7], s[14:15], v0, s55, v[10:11]
	ds_read_b128 v[6:9], v6
	s_waitcnt lgkmcnt(1)
	global_store_dwordx4 v[14:15], v[2:5], off nt
	v_readlane_b32 s10, v252, 12
	s_add_i32 s23, s23, s10
	v_add_u32_e32 v2, s12, v0
	v_ashrrev_i32_e32 v3, 31, v2
	v_lshlrev_b64 v[2:3], 11, v[2:3]
	v_add_u32_e32 v0, 0x200, v189
	v_lshl_add_u64 v[2:3], v[12:13], 0, v[2:3]
	v_ashrrev_i32_e32 v0, 5, v0
	s_waitcnt lgkmcnt(0)
	global_store_dwordx4 v[2:3], v[6:9], off nt
	v_mad_u64_u32 v[2:3], s[14:15], v0, s55, v[10:11]
	ds_read_b128 v[2:5], v2
	v_add_u32_e32 v6, s12, v0
	v_ashrrev_i32_e32 v7, 31, v6
	v_add_u32_e32 v0, 0x300, v189
	v_lshlrev_b64 v[6:7], 11, v[6:7]
	v_ashrrev_i32_e32 v0, 5, v0
	v_lshl_add_u64 v[14:15], v[12:13], 0, v[6:7]
	v_mad_u64_u32 v[6:7], s[14:15], v0, s55, v[10:11]
	ds_read_b128 v[6:9], v6
	s_waitcnt lgkmcnt(1)
	global_store_dwordx4 v[14:15], v[2:5], off nt
	s_cmp_ge_i32 s23, s16
	s_nop 0
	v_add_u32_e32 v2, s12, v0
	v_ashrrev_i32_e32 v3, 31, v2
	v_lshlrev_b64 v[2:3], 11, v[2:3]
	v_add_u32_e32 v0, 0x400, v189
	v_lshl_add_u64 v[2:3], v[12:13], 0, v[2:3]
	v_ashrrev_i32_e32 v0, 5, v0
	s_waitcnt lgkmcnt(0)
	global_store_dwordx4 v[2:3], v[6:9], off nt
	v_mad_u64_u32 v[2:3], s[14:15], v0, s55, v[10:11]
	ds_read_b128 v[2:5], v2
	v_add_u32_e32 v6, s12, v0
	v_ashrrev_i32_e32 v7, 31, v6
	v_add_u32_e32 v0, 0x500, v189
	v_lshlrev_b64 v[6:7], 11, v[6:7]
	v_ashrrev_i32_e32 v0, 5, v0
	v_lshl_add_u64 v[14:15], v[12:13], 0, v[6:7]
	v_mad_u64_u32 v[6:7], s[14:15], v0, s55, v[10:11]
	ds_read_b128 v[6:9], v6
	s_waitcnt lgkmcnt(1)
	global_store_dwordx4 v[14:15], v[2:5], off nt
	s_nop 1
	v_add_u32_e32 v2, s12, v0
	v_ashrrev_i32_e32 v3, 31, v2
	v_lshlrev_b64 v[2:3], 11, v[2:3]
	v_add_u32_e32 v0, 0x600, v189
	v_lshl_add_u64 v[2:3], v[12:13], 0, v[2:3]
	v_ashrrev_i32_e32 v0, 5, v0
	s_waitcnt lgkmcnt(0)
	global_store_dwordx4 v[2:3], v[6:9], off nt
	v_mad_u64_u32 v[2:3], s[14:15], v0, s55, v[10:11]
	ds_read_b128 v[2:5], v2
	v_add_u32_e32 v6, s12, v0
	v_ashrrev_i32_e32 v7, 31, v6
	v_add_u32_e32 v0, 0x700, v189
	v_lshlrev_b64 v[6:7], 11, v[6:7]
	v_ashrrev_i32_e32 v0, 5, v0
	v_lshl_add_u64 v[14:15], v[12:13], 0, v[6:7]
	v_mad_u64_u32 v[6:7], s[14:15], v0, s55, v[10:11]
	ds_read_b128 v[6:9], v6
	s_waitcnt lgkmcnt(1)
	global_store_dwordx4 v[14:15], v[2:5], off nt
	s_nop 1
	v_add_u32_e32 v2, s12, v0
	v_ashrrev_i32_e32 v3, 31, v2
	v_lshlrev_b64 v[2:3], 11, v[2:3]
	v_add_u32_e32 v0, 0x800, v189
	v_lshl_add_u64 v[2:3], v[12:13], 0, v[2:3]
	v_ashrrev_i32_e32 v0, 5, v0
	s_waitcnt lgkmcnt(0)
	global_store_dwordx4 v[2:3], v[6:9], off nt
	v_mad_u64_u32 v[2:3], s[14:15], v0, s55, v[10:11]
	ds_read_b128 v[2:5], v2
	v_add_u32_e32 v6, s12, v0
	v_ashrrev_i32_e32 v7, 31, v6
	v_add_u32_e32 v0, 0x900, v189
	v_lshlrev_b64 v[6:7], 11, v[6:7]
	v_ashrrev_i32_e32 v0, 5, v0
	v_lshl_add_u64 v[14:15], v[12:13], 0, v[6:7]
	v_mad_u64_u32 v[6:7], s[14:15], v0, s55, v[10:11]
	ds_read_b128 v[6:9], v6
	s_waitcnt lgkmcnt(1)
	global_store_dwordx4 v[14:15], v[2:5], off nt
	s_nop 1
	v_add_u32_e32 v2, s12, v0
	v_ashrrev_i32_e32 v3, 31, v2
	v_lshlrev_b64 v[2:3], 11, v[2:3]
	v_add_u32_e32 v0, 0xa00, v189
	v_lshl_add_u64 v[2:3], v[12:13], 0, v[2:3]
	v_ashrrev_i32_e32 v0, 5, v0
	s_waitcnt lgkmcnt(0)
	global_store_dwordx4 v[2:3], v[6:9], off nt
	v_mad_u64_u32 v[2:3], s[14:15], v0, s55, v[10:11]
	ds_read_b128 v[2:5], v2
	v_add_u32_e32 v6, s12, v0
	v_ashrrev_i32_e32 v7, 31, v6
	v_add_u32_e32 v0, 0xb00, v189
	v_lshlrev_b64 v[6:7], 11, v[6:7]
	v_ashrrev_i32_e32 v0, 5, v0
	v_lshl_add_u64 v[14:15], v[12:13], 0, v[6:7]
	v_mad_u64_u32 v[6:7], s[14:15], v0, s55, v[10:11]
	ds_read_b128 v[6:9], v6
	s_waitcnt lgkmcnt(1)
	global_store_dwordx4 v[14:15], v[2:5], off nt
	s_nop 1
	v_add_u32_e32 v2, s12, v0
	v_ashrrev_i32_e32 v3, 31, v2
	v_lshlrev_b64 v[2:3], 11, v[2:3]
	v_add_u32_e32 v0, 0xc00, v189
	v_lshl_add_u64 v[2:3], v[12:13], 0, v[2:3]
	v_ashrrev_i32_e32 v0, 5, v0
	s_waitcnt lgkmcnt(0)
	global_store_dwordx4 v[2:3], v[6:9], off nt
	v_mad_u64_u32 v[2:3], s[14:15], v0, s55, v[10:11]
	ds_read_b128 v[2:5], v2
	v_add_u32_e32 v6, s12, v0
	v_ashrrev_i32_e32 v7, 31, v6
	v_add_u32_e32 v0, 0xd00, v189
	v_lshlrev_b64 v[6:7], 11, v[6:7]
	v_ashrrev_i32_e32 v0, 5, v0
	v_lshl_add_u64 v[14:15], v[12:13], 0, v[6:7]
	v_mad_u64_u32 v[6:7], s[14:15], v0, s55, v[10:11]
	ds_read_b128 v[6:9], v6
	s_waitcnt lgkmcnt(1)
	global_store_dwordx4 v[14:15], v[2:5], off nt
	s_nop 1
	v_add_u32_e32 v2, s12, v0
	v_ashrrev_i32_e32 v3, 31, v2
	v_lshlrev_b64 v[2:3], 11, v[2:3]
	v_add_u32_e32 v0, 0xe00, v189
	v_lshl_add_u64 v[2:3], v[12:13], 0, v[2:3]
	v_ashrrev_i32_e32 v0, 5, v0
	s_waitcnt lgkmcnt(0)
	global_store_dwordx4 v[2:3], v[6:9], off nt
	v_mad_u64_u32 v[2:3], s[14:15], v0, s55, v[10:11]
	ds_read_b128 v[2:5], v2
	v_add_u32_e32 v6, s12, v0
	v_ashrrev_i32_e32 v7, 31, v6
	v_add_u32_e32 v0, 0xf00, v189
	v_lshlrev_b64 v[6:7], 11, v[6:7]
	v_ashrrev_i32_e32 v0, 5, v0
	v_lshl_add_u64 v[14:15], v[12:13], 0, v[6:7]
	v_mad_u64_u32 v[6:7], s[14:15], v0, s55, v[10:11]
	ds_read_b128 v[6:9], v6
	s_waitcnt lgkmcnt(1)
	global_store_dwordx4 v[14:15], v[2:5], off nt
	s_nop 1
	v_add_u32_e32 v2, s12, v0
	v_ashrrev_i32_e32 v3, 31, v2
	v_lshlrev_b64 v[2:3], 11, v[2:3]
	v_lshl_add_u64 v[2:3], v[12:13], 0, v[2:3]
	s_waitcnt lgkmcnt(0)
	global_store_dwordx4 v[2:3], v[6:9], off nt
	s_barrier
	s_cbranch_scc0 .LBB0_20

; #define LAS __attribute__((address_space(3)))
; DI f32x16 mfma32(bf16x8 a, bf16x8 b, f32x16 c) { return __builtin_amdgcn_mfma_f32_32x32x16_bf16(a, b, c, 0, 0, 0); }
;     ...
;   for (int kt = 0; kt < nk; ++kt) {
;     const int kn = (kt + 2 < nk) ? (kt + 2) : (nk - 1);
;     const LAS char* cur = lds + s0;
;     bf16x8 af[2][2], bfr[2][4];
; #pragma unroll
;     for (int kk = 0; kk < 2; ++kk) {
;       const int xo = kk ? x1 : x0;
;       af[kk][0] = *(const LAS bf16x8*)(cur + a_rd + xo);
;       bfr[kk][0] = *(const LAS bf16x8*)(cur + b_rd + xo);
;       bfr[kk][1] = *(const LAS bf16x8*)(cur + b_rd + 2048 + xo);
;       af[kk][1] = *(const LAS bf16x8*)(cur + a_rd + 2048 + xo);
;       bfr[kk][2] = *(const LAS bf16x8*)(cur + b_rd + 4096 + xo);
;       bfr[kk][3] = *(const LAS bf16x8*)(cur + b_rd + 6144 + xo);
;     }
;     DMA_STEP_(kn, s2);
; #pragma unroll
;     for (int kk = 0; kk < 2; ++kk) {
;       acc[0][0] = mfma32(bfr[kk][0], af[kk][0], acc[0][0]); acc[0][1] = mfma32(bfr[kk][1], af[kk][0], acc[0][1]);
;       acc[1][0] = mfma32(bfr[kk][0], af[kk][1], acc[1][0]); acc[1][1] = mfma32(bfr[kk][1], af[kk][1], acc[1][1]);
;       acc[0][2] = mfma32(bfr[kk][2], af[kk][0], acc[0][2]); acc[0][3] = mfma32(bfr[kk][3], af[kk][0], acc[0][3]);
;       acc[1][2] = mfma32(bfr[kk][2], af[kk][1], acc[1][2]); acc[1][3] = mfma32(bfr[kk][3], af[kk][1], acc[1][3]);
;     }
;     __builtin_amdgcn_sched_group_barrier(0x100, 12, 0);
;     __builtin_amdgcn_sched_group_barrier(0x010, 6, 0);
;     __builtin_amdgcn_sched_group_barrier(0x008, 16, 0);
;     asm volatile("s_waitcnt vmcnt(6) lgkmcnt(0)" ::: "memory");
;     __builtin_amdgcn_s_barrier();
;     asm volatile("" ::: "memory");
;     s0 = (s0 == 2 * STG) ? 0 : s0 + STG;
;     s2 = (s2 == 2 * STG) ? 0 : s2 + STG;
;   }
.LBB0_184:
	s_add_i32 s11, s29, 16
	s_mov_b32 s10, s23
	v_add_u32_e32 v142, s11, v219
	v_add_u32_e32 v150, s11, v218
	s_min_u32 s10, s10, 29
	v_add_u32_e32 v142, v142, v220
	v_add_u32_e32 v150, v150, v220
	s_lshl_b32 s70, s10, 6
	ds_read_b128 v[138:141], v142
	ds_read_b128 v[162:165], v150 offset:8192
	ds_read_b128 v[166:169], v150 offset:10240
	ds_read_b128 v[142:145], v142 offset:2048
	ds_read_b128 v[146:149], v150 offset:12288
	ds_read_b128 v[150:153], v150 offset:14336
	s_mul_i32 vcc_lo, s70, 0x12000
	s_add_i32 s10, s13, s28
	v_lshl_add_u64 v[222:223], v[192:193], 0, vcc
	s_mov_b32 m0, s10
	s_mul_i32 s100, s70, 0x900
	v_lshl_add_u64 v[224:225], v[194:195], 0, s[100:101]
	s_add_i32 s10, s22, s28
	s_waitcnt lgkmcnt(6)
	v_mfma_f32_32x32x16_bf16 v[114:129], v[182:185], v[154:157], v[114:129]
	global_load_lds_dwordx4 v[222:223], off
	v_mfma_f32_32x32x16_bf16 v[98:113], v[178:181], v[154:157], v[98:113]
	global_load_lds_dwordx4 v[222:223], off offset:1024
	s_add_i32 m0, s10, 0x2000
	v_mfma_f32_32x32x16_bf16 v[66:81], v[182:185], v[158:161], v[66:81]
	global_load_lds_dwordx4 v[224:225], off
	v_mfma_f32_32x32x16_bf16 v[34:49], v[178:181], v[158:161], v[34:49]
	global_load_lds_dwordx4 v[224:225], off offset:1024
	v_mfma_f32_32x32x16_bf16 v[82:97], v[174:177], v[154:157], v[82:97]
	global_load_lds_dwordx4 v[224:225], off offset:2048
	v_mfma_f32_32x32x16_bf16 v[50:65], v[170:173], v[154:157], v[50:65]
	global_load_lds_dwordx4 v[224:225], off offset:3072
	v_mfma_f32_32x32x16_bf16 v[18:33], v[174:177], v[158:161], v[18:33]
	s_add_i32 s10, s29, 0x6000
	s_cmpk_lg_u32 s29, 0xc000
	s_cselect_b32 s29, s10, 0
	s_add_i32 s10, s28, 0x6000
	s_cmpk_lg_u32 s28, 0xc000
	s_cselect_b32 s28, s10, 0
	v_mfma_f32_32x32x16_bf16 v[2:17], v[170:173], v[158:161], v[2:17]
	s_add_i32 s11, s29, 16
	s_waitcnt vmcnt(6) lgkmcnt(0)
	s_barrier
	v_add_u32_e32 v158, s11, v219
	v_add_u32_e32 v170, s11, v218
	v_add_u32_e32 v158, v158, v0
	v_add_u32_e32 v170, v170, v0
	ds_read_b128 v[154:157], v158
	ds_read_b128 v[182:185], v170 offset:8192
	ds_read_b128 v[178:181], v170 offset:10240
	ds_read_b128 v[158:161], v158 offset:2048
	ds_read_b128 v[174:177], v170 offset:12288
	ds_read_b128 v[170:173], v170 offset:14336
	v_mfma_f32_32x32x16_bf16 v[114:129], v[162:165], v[138:141], v[114:129]
	v_mfma_f32_32x32x16_bf16 v[98:113], v[166:169], v[138:141], v[98:113]
	v_mfma_f32_32x32x16_bf16 v[66:81], v[162:165], v[142:145], v[66:81]
	v_mfma_f32_32x32x16_bf16 v[34:49], v[166:169], v[142:145], v[34:49]
	v_mfma_f32_32x32x16_bf16 v[82:97], v[146:149], v[138:141], v[82:97]
	v_mfma_f32_32x32x16_bf16 v[50:65], v[150:153], v[138:141], v[50:65]
	v_mfma_f32_32x32x16_bf16 v[18:33], v[146:149], v[142:145], v[18:33]
	v_mfma_f32_32x32x16_bf16 v[2:17], v[150:153], v[142:145], v[2:17]
	s_add_i32 s11, s29, 16
	s_add_i32 s10, s23, 1
	v_add_u32_e32 v142, s11, v219
	v_add_u32_e32 v150, s11, v218
	s_min_u32 s10, s10, 29
	v_add_u32_e32 v142, v142, v220
	v_add_u32_e32 v150, v150, v220
	s_lshl_b32 s70, s10, 6
	ds_read_b128 v[138:141], v142
	ds_read_b128 v[162:165], v150 offset:8192
	ds_read_b128 v[166:169], v150 offset:10240
	ds_read_b128 v[142:145], v142 offset:2048
	ds_read_b128 v[146:149], v150 offset:12288
	ds_read_b128 v[150:153], v150 offset:14336
	s_mul_i32 vcc_lo, s70, 0x12000
	s_add_i32 s10, s13, s28
	v_lshl_add_u64 v[222:223], v[192:193], 0, vcc
	s_mov_b32 m0, s10
	s_mul_i32 s100, s70, 0x900
	v_lshl_add_u64 v[224:225], v[194:195], 0, s[100:101]
	s_add_i32 s10, s22, s28
	s_waitcnt lgkmcnt(6)
	v_mfma_f32_32x32x16_bf16 v[114:129], v[182:185], v[154:157], v[114:129]
	global_load_lds_dwordx4 v[222:223], off
	v_mfma_f32_32x32x16_bf16 v[98:113], v[178:181], v[154:157], v[98:113]
	global_load_lds_dwordx4 v[222:223], off offset:1024
	s_add_i32 m0, s10, 0x2000
	v_mfma_f32_32x32x16_bf16 v[66:81], v[182:185], v[158:161], v[66:81]
	global_load_lds_dwordx4 v[224:225], off
	v_mfma_f32_32x32x16_bf16 v[34:49], v[178:181], v[158:161], v[34:49]
	global_load_lds_dwordx4 v[224:225], off offset:1024
	v_mfma_f32_32x32x16_bf16 v[82:97], v[174:177], v[154:157], v[82:97]
	global_load_lds_dwordx4 v[224:225], off offset:2048
	v_mfma_f32_32x32x16_bf16 v[50:65], v[170:173], v[154:157], v[50:65]
	global_load_lds_dwordx4 v[224:225], off offset:3072
	v_mfma_f32_32x32x16_bf16 v[18:33], v[174:177], v[158:161], v[18:33]
	s_add_i32 s10, s29, 0x6000
	s_cmpk_lg_u32 s29, 0xc000
	s_cselect_b32 s29, s10, 0
	s_add_i32 s10, s28, 0x6000
	s_cmpk_lg_u32 s28, 0xc000
	s_cselect_b32 s28, s10, 0
	v_mfma_f32_32x32x16_bf16 v[2:17], v[170:173], v[158:161], v[2:17]
	s_add_i32 s11, s29, 16
	s_waitcnt vmcnt(6) lgkmcnt(0)
	s_barrier
	v_add_u32_e32 v158, s11, v219
	v_add_u32_e32 v170, s11, v218
	v_add_u32_e32 v158, v158, v0
	v_add_u32_e32 v170, v170, v0
	ds_read_b128 v[154:157], v158
	ds_read_b128 v[182:185], v170 offset:8192
	ds_read_b128 v[178:181], v170 offset:10240
	ds_read_b128 v[158:161], v158 offset:2048
	ds_read_b128 v[174:177], v170 offset:12288
	ds_read_b128 v[170:173], v170 offset:14336
	v_mfma_f32_32x32x16_bf16 v[114:129], v[162:165], v[138:141], v[114:129]
	v_mfma_f32_32x32x16_bf16 v[98:113], v[166:169], v[138:141], v[98:113]
	v_mfma_f32_32x32x16_bf16 v[66:81], v[162:165], v[142:145], v[66:81]
	v_mfma_f32_32x32x16_bf16 v[34:49], v[166:169], v[142:145], v[34:49]
	v_mfma_f32_32x32x16_bf16 v[82:97], v[146:149], v[138:141], v[82:97]
	v_mfma_f32_32x32x16_bf16 v[50:65], v[150:153], v[138:141], v[50:65]
	v_mfma_f32_32x32x16_bf16 v[18:33], v[146:149], v[142:145], v[18:33]
	v_mfma_f32_32x32x16_bf16 v[2:17], v[150:153], v[142:145], v[2:17]
	s_add_i32 s23, s23, 2
	s_cmp_lg_u32 s23, 32
	s_cbranch_scc1 .LBB0_184
; DI unsigned pk2(float a, float b) { f32x2 v = {a, b}; bf2_t r = __builtin_convertvector(v, bf2_t); return __builtin_bit_cast(unsigned, r); }
;     ...
;   asm volatile("s_waitcnt vmcnt(0)" ::: "memory");
;   __builtin_amdgcn_s_barrier();
;   asm volatile("" ::: "memory");
;     ...
;   {
;     const int h = lane >> 5, cl = lane & 31;
; #pragma unroll
;     for (int i = 0; i < 2; ++i)
; #pragma unroll
;       for (int j = 0; j < 4; ++j)
; #pragma unroll
;         for (int g = 0; g < 4; ++g) {
;           u32x2 w; w.x = pk2(acc[i][j][4 * g], acc[i][j][4 * g + 1]); w.y = pk2(acc[i][j][4 * g + 2], acc[i][j][4 * g + 3]);
;           *(u32x2*)(smem + (wr * 64 + i * 32 + cl) * 528 + (wc * 128 + j * 32 + 8 * g + 4 * h) * 2) = w;
;         }
;   }
;   __syncthreads();
	s_waitcnt lgkmcnt(0)
	s_setprio 0
	v_mul_lo_u32 v0, v197, s55
	v_add_u32_e32 v0, 16, v0
	s_nop 1
	v_cvt_pk_bf16_f32 v114, v114, v115
	v_cvt_pk_bf16_f32 v115, v116, v117
	v_lshlrev_b32_e32 v116, 3, v196
	s_lshl_b32 s10, s21, 1
	v_add3_u32 v0, v0, v116, s10
	v_cvt_pk_bf16_f32 v116, v118, v119
	v_cvt_pk_bf16_f32 v117, v120, v121
	v_cvt_pk_bf16_f32 v98, v98, v99
	v_cvt_pk_bf16_f32 v99, v100, v101
	v_cvt_pk_bf16_f32 v100, v102, v103
	v_cvt_pk_bf16_f32 v101, v104, v105
	v_cvt_pk_bf16_f32 v82, v82, v83
	v_cvt_pk_bf16_f32 v83, v84, v85
	v_cvt_pk_bf16_f32 v84, v86, v87
	v_cvt_pk_bf16_f32 v85, v88, v89
	v_cvt_pk_bf16_f32 v50, v50, v51
	v_cvt_pk_bf16_f32 v51, v52, v53
	v_cvt_pk_bf16_f32 v52, v54, v55
	v_cvt_pk_bf16_f32 v53, v56, v57
	s_waitcnt vmcnt(0)
	s_barrier
	ds_write2_b64 v0, v[114:115], v[116:117] offset1:2
	v_cvt_pk_bf16_f32 v114, v122, v123
	v_cvt_pk_bf16_f32 v115, v124, v125
	v_cvt_pk_bf16_f32 v116, v126, v127
	v_cvt_pk_bf16_f32 v117, v128, v129
	ds_write2_b64 v0, v[98:99], v[100:101] offset0:8 offset1:10
	v_cvt_pk_bf16_f32 v98, v106, v107
	v_cvt_pk_bf16_f32 v99, v108, v109
	v_cvt_pk_bf16_f32 v100, v110, v111
	v_cvt_pk_bf16_f32 v101, v112, v113
	ds_write2_b64 v0, v[82:83], v[84:85] offset0:16 offset1:18
	v_cvt_pk_bf16_f32 v82, v90, v91
	v_cvt_pk_bf16_f32 v83, v92, v93
	v_cvt_pk_bf16_f32 v84, v94, v95
	v_cvt_pk_bf16_f32 v85, v96, v97
	ds_write2_b64 v0, v[50:51], v[52:53] offset0:24 offset1:26
	v_cvt_pk_bf16_f32 v50, v58, v59
	v_cvt_pk_bf16_f32 v51, v60, v61
	v_cvt_pk_bf16_f32 v52, v62, v63
	v_cvt_pk_bf16_f32 v53, v64, v65
	ds_write2_b64 v0, v[114:115], v[116:117] offset0:4 offset1:6
	ds_write2_b64 v0, v[98:99], v[100:101] offset0:12 offset1:14
	ds_write2_b64 v0, v[82:83], v[84:85] offset0:20 offset1:22
	ds_write2_b64 v0, v[50:51], v[52:53] offset0:28 offset1:30
	v_cvt_pk_bf16_f32 v50, v66, v67
	v_cvt_pk_bf16_f32 v51, v68, v69
	v_cvt_pk_bf16_f32 v52, v70, v71
	v_cvt_pk_bf16_f32 v53, v72, v73
	v_add_u32_e32 v0, 0x4000, v0
	v_cvt_pk_bf16_f32 v34, v34, v35
	v_cvt_pk_bf16_f32 v35, v36, v37
	v_cvt_pk_bf16_f32 v36, v38, v39
	v_cvt_pk_bf16_f32 v37, v40, v41
	v_cvt_pk_bf16_f32 v18, v18, v19
	v_cvt_pk_bf16_f32 v19, v20, v21
	v_cvt_pk_bf16_f32 v20, v22, v23
	v_cvt_pk_bf16_f32 v21, v24, v25
	v_cvt_pk_bf16_f32 v2, v2, v3
	v_cvt_pk_bf16_f32 v3, v4, v5
	v_cvt_pk_bf16_f32 v4, v6, v7
	v_cvt_pk_bf16_f32 v5, v8, v9
	ds_write2_b64 v0, v[50:51], v[52:53] offset0:64 offset1:66
	v_cvt_pk_bf16_f32 v50, v74, v75
	v_cvt_pk_bf16_f32 v51, v76, v77
	v_cvt_pk_bf16_f32 v52, v78, v79
	v_cvt_pk_bf16_f32 v53, v80, v81
	ds_write2_b64 v0, v[34:35], v[36:37] offset0:72 offset1:74
	v_cvt_pk_bf16_f32 v34, v42, v43
	v_cvt_pk_bf16_f32 v35, v44, v45
	v_cvt_pk_bf16_f32 v36, v46, v47
	v_cvt_pk_bf16_f32 v37, v48, v49
	ds_write2_b64 v0, v[18:19], v[20:21] offset0:80 offset1:82
	v_cvt_pk_bf16_f32 v18, v26, v27
	v_cvt_pk_bf16_f32 v19, v28, v29
	v_cvt_pk_bf16_f32 v20, v30, v31
	v_cvt_pk_bf16_f32 v21, v32, v33
	ds_write2_b64 v0, v[2:3], v[4:5] offset0:88 offset1:90
	v_cvt_pk_bf16_f32 v2, v10, v11
	v_cvt_pk_bf16_f32 v3, v12, v13
	v_cvt_pk_bf16_f32 v4, v14, v15
	v_cvt_pk_bf16_f32 v5, v16, v17
	s_lshl_b64 s[14:15], s[14:15], 1
	ds_write2_b64 v0, v[50:51], v[52:53] offset0:68 offset1:70
	ds_write2_b64 v0, v[34:35], v[36:37] offset0:76 offset1:78
	ds_write2_b64 v0, v[18:19], v[20:21] offset0:84 offset1:86
	ds_write2_b64 v0, v[2:3], v[4:5] offset0:92 offset1:94
	s_waitcnt vmcnt(0) lgkmcnt(0)
	s_barrier
; #define GAS __attribute__((address_space(1)))
;     ...
;   int tid2 = tid; asm volatile("" : "+v"(tid2));
;   if (EPI == 0) {
; #pragma unroll
;     for (int i = 0; i < 16; ++i) {
;       const int id = tid2 + 256 * i, r = id >> 5, c8 = (id & 31) * 8;
;       const u32x4 v = *(const u32x4*)(smem + r * 528 + c8 * 2);
;       *(GAS u32x4*)(ea.out + (size_t)(m0 + r) * ea.ldo + n0 + c8) = v;
;     }
	s_add_u32 s14, s16, s14
	v_lshlrev_b32_e32 v0, 4, v189
	v_and_b32_e32 v0, 0x1f0, v0
	s_addc_u32 s15, s17, s15
	v_add_u32_e32 v10, 16, v0
	v_lshl_add_u64 v[12:13], s[14:15], 0, v[0:1]
	v_ashrrev_i32_e32 v0, 5, v189
	v_mad_u64_u32 v[2:3], s[14:15], v0, s55, v[10:11]
	v_add_u32_e32 v0, s12, v0
	v_mad_i64_i32 v[14:15], s[14:15], v0, s35, v[12:13]
	v_add_u32_e32 v0, 0x100, v189
	ds_read_b128 v[2:5], v2
	v_ashrrev_i32_e32 v0, 5, v0
	v_mad_u64_u32 v[6:7], s[14:15], v0, s55, v[10:11]
	ds_read_b128 v[6:9], v6
	v_add_u32_e32 v0, s12, v0
	s_waitcnt lgkmcnt(1)
	global_store_dwordx4 v[14:15], v[2:5], off nt
	v_readlane_b32 s10, v252, 12
	s_add_i32 s20, s20, s10
	v_mad_i64_i32 v[2:3], s[14:15], v0, s35, v[12:13]
	v_add_u32_e32 v0, 0x200, v189
	v_ashrrev_i32_e32 v0, 5, v0
	s_waitcnt lgkmcnt(0)
	global_store_dwordx4 v[2:3], v[6:9], off nt
	v_mad_u64_u32 v[2:3], s[14:15], v0, s55, v[10:11]
	v_add_u32_e32 v0, s12, v0
	v_mad_i64_i32 v[14:15], s[14:15], v0, s35, v[12:13]
	v_add_u32_e32 v0, 0x300, v189
	ds_read_b128 v[2:5], v2
	v_ashrrev_i32_e32 v0, 5, v0
	v_mad_u64_u32 v[6:7], s[14:15], v0, s55, v[10:11]
	ds_read_b128 v[6:9], v6
	v_add_u32_e32 v0, s12, v0
	s_waitcnt lgkmcnt(1)
	global_store_dwordx4 v[14:15], v[2:5], off nt
	s_cmp_ge_i32 s20, s45
	s_nop 0
	v_mad_i64_i32 v[2:3], s[14:15], v0, s35, v[12:13]
	v_add_u32_e32 v0, 0x400, v189
	v_ashrrev_i32_e32 v0, 5, v0
	s_waitcnt lgkmcnt(0)
	global_store_dwordx4 v[2:3], v[6:9], off nt
	v_mad_u64_u32 v[2:3], s[14:15], v0, s55, v[10:11]
	v_add_u32_e32 v0, s12, v0
	v_mad_i64_i32 v[14:15], s[14:15], v0, s35, v[12:13]
	v_add_u32_e32 v0, 0x500, v189
	ds_read_b128 v[2:5], v2
	v_ashrrev_i32_e32 v0, 5, v0
	v_mad_u64_u32 v[6:7], s[14:15], v0, s55, v[10:11]
	ds_read_b128 v[6:9], v6
	v_add_u32_e32 v0, s12, v0
	s_waitcnt lgkmcnt(1)
	global_store_dwordx4 v[14:15], v[2:5], off nt
	s_nop 1
	v_mad_i64_i32 v[2:3], s[14:15], v0, s35, v[12:13]
	v_add_u32_e32 v0, 0x600, v189
	v_ashrrev_i32_e32 v0, 5, v0
	s_waitcnt lgkmcnt(0)
	global_store_dwordx4 v[2:3], v[6:9], off nt
	v_mad_u64_u32 v[2:3], s[14:15], v0, s55, v[10:11]
	v_add_u32_e32 v0, s12, v0
	v_mad_i64_i32 v[14:15], s[14:15], v0, s35, v[12:13]
	v_add_u32_e32 v0, 0x700, v189
	ds_read_b128 v[2:5], v2
	v_ashrrev_i32_e32 v0, 5, v0
	v_mad_u64_u32 v[6:7], s[14:15], v0, s55, v[10:11]
	ds_read_b128 v[6:9], v6
	v_add_u32_e32 v0, s12, v0
	s_waitcnt lgkmcnt(1)
	global_store_dwordx4 v[14:15], v[2:5], off nt
	s_nop 1
	v_mad_i64_i32 v[2:3], s[14:15], v0, s35, v[12:13]
	v_add_u32_e32 v0, 0x800, v189
	v_ashrrev_i32_e32 v0, 5, v0
	s_waitcnt lgkmcnt(0)
	global_store_dwordx4 v[2:3], v[6:9], off nt
	v_mad_u64_u32 v[2:3], s[14:15], v0, s55, v[10:11]
	v_add_u32_e32 v0, s12, v0
	v_mad_i64_i32 v[14:15], s[14:15], v0, s35, v[12:13]
	v_add_u32_e32 v0, 0x900, v189
	ds_read_b128 v[2:5], v2
	v_ashrrev_i32_e32 v0, 5, v0
	v_mad_u64_u32 v[6:7], s[14:15], v0, s55, v[10:11]
	ds_read_b128 v[6:9], v6
	v_add_u32_e32 v0, s12, v0
	s_waitcnt lgkmcnt(1)
	global_store_dwordx4 v[14:15], v[2:5], off nt
	s_nop 1
	v_mad_i64_i32 v[2:3], s[14:15], v0, s35, v[12:13]
	v_add_u32_e32 v0, 0xa00, v189
	v_ashrrev_i32_e32 v0, 5, v0
	s_waitcnt lgkmcnt(0)
	global_store_dwordx4 v[2:3], v[6:9], off nt
	v_mad_u64_u32 v[2:3], s[14:15], v0, s55, v[10:11]
	v_add_u32_e32 v0, s12, v0
	v_mad_i64_i32 v[14:15], s[14:15], v0, s35, v[12:13]
	v_add_u32_e32 v0, 0xb00, v189
	ds_read_b128 v[2:5], v2
	v_ashrrev_i32_e32 v0, 5, v0
	v_mad_u64_u32 v[6:7], s[14:15], v0, s55, v[10:11]
	ds_read_b128 v[6:9], v6
	v_add_u32_e32 v0, s12, v0
	s_waitcnt lgkmcnt(1)
	global_store_dwordx4 v[14:15], v[2:5], off nt
	s_nop 1
	v_mad_i64_i32 v[2:3], s[14:15], v0, s35, v[12:13]
	v_add_u32_e32 v0, 0xc00, v189
	v_ashrrev_i32_e32 v0, 5, v0
	s_waitcnt lgkmcnt(0)
	global_store_dwordx4 v[2:3], v[6:9], off nt
	v_mad_u64_u32 v[2:3], s[14:15], v0, s55, v[10:11]
	v_add_u32_e32 v0, s12, v0
	v_mad_i64_i32 v[14:15], s[14:15], v0, s35, v[12:13]
	v_add_u32_e32 v0, 0xd00, v189
	ds_read_b128 v[2:5], v2
	v_ashrrev_i32_e32 v0, 5, v0
	v_mad_u64_u32 v[6:7], s[14:15], v0, s55, v[10:11]
	ds_read_b128 v[6:9], v6
	v_add_u32_e32 v0, s12, v0
	s_waitcnt lgkmcnt(1)
	global_store_dwordx4 v[14:15], v[2:5], off nt
	s_nop 1
	v_mad_i64_i32 v[2:3], s[14:15], v0, s35, v[12:13]
	v_add_u32_e32 v0, 0xe00, v189
	v_ashrrev_i32_e32 v0, 5, v0
	s_waitcnt lgkmcnt(0)
	global_store_dwordx4 v[2:3], v[6:9], off nt
	v_mad_u64_u32 v[2:3], s[14:15], v0, s55, v[10:11]
	v_add_u32_e32 v0, s12, v0
	v_mad_i64_i32 v[14:15], s[14:15], v0, s35, v[12:13]
	v_add_u32_e32 v0, 0xf00, v189
	v_ashrrev_i32_e32 v0, 5, v0
	ds_read_b128 v[2:5], v2
	v_mad_u64_u32 v[6:7], s[14:15], v0, s55, v[10:11]
	ds_read_b128 v[6:9], v6
	v_add_u32_e32 v0, s12, v0
	s_waitcnt lgkmcnt(1)
	global_store_dwordx4 v[14:15], v[2:5], off nt
	s_nop 1
	v_mad_i64_i32 v[2:3], s[12:13], v0, s35, v[12:13]
	s_waitcnt lgkmcnt(0)
	global_store_dwordx4 v[2:3], v[6:9], off nt
	s_barrier
	s_cbranch_scc0 .LBB0_183
	v_mov_b64_e32 v[6:7], v[130:131]
	v_mov_b64_e32 v[2:3], v[134:135]
	v_mov_b32_e32 v31, v214
	v_mov_b32_e32 v30, v215
	v_mov_b32_e32 v29, v216
	v_mov_b32_e32 v28, v217
	v_mov_b64_e32 v[8:9], v[132:133]
	v_mov_b64_e32 v[4:5], v[136:137]
	v_readlane_b32 s44, v250, 17

; #define LAS __attribute__((address_space(3)))
; DI f32x16 mfma32(bf16x8 a, bf16x8 b, f32x16 c) { return __builtin_amdgcn_mfma_f32_32x32x16_bf16(a, b, c, 0, 0, 0); }
;     ...
;   for (int kt = 0; kt < nk; ++kt) {
;     const int kn = (kt + 2 < nk) ? (kt + 2) : (nk - 1);
;     const LAS char* cur = lds + s0;
;     bf16x8 af[2][2], bfr[2][4];
; #pragma unroll
;     for (int kk = 0; kk < 2; ++kk) {
;       const int xo = kk ? x1 : x0;
;       af[kk][0] = *(const LAS bf16x8*)(cur + a_rd + xo);
;       bfr[kk][0] = *(const LAS bf16x8*)(cur + b_rd + xo);
;       bfr[kk][1] = *(const LAS bf16x8*)(cur + b_rd + 2048 + xo);
;       af[kk][1] = *(const LAS bf16x8*)(cur + a_rd + 2048 + xo);
;       bfr[kk][2] = *(const LAS bf16x8*)(cur + b_rd + 4096 + xo);
;       bfr[kk][3] = *(const LAS bf16x8*)(cur + b_rd + 6144 + xo);
;     }
;     DMA_STEP_(kn, s2);
; #pragma unroll
;     for (int kk = 0; kk < 2; ++kk) {
;       acc[0][0] = mfma32(bfr[kk][0], af[kk][0], acc[0][0]); acc[0][1] = mfma32(bfr[kk][1], af[kk][0], acc[0][1]);
;       acc[1][0] = mfma32(bfr[kk][0], af[kk][1], acc[1][0]); acc[1][1] = mfma32(bfr[kk][1], af[kk][1], acc[1][1]);
;       acc[0][2] = mfma32(bfr[kk][2], af[kk][0], acc[0][2]); acc[0][3] = mfma32(bfr[kk][3], af[kk][0], acc[0][3]);
;       acc[1][2] = mfma32(bfr[kk][2], af[kk][1], acc[1][2]); acc[1][3] = mfma32(bfr[kk][3], af[kk][1], acc[1][3]);
;     }
;     __builtin_amdgcn_sched_group_barrier(0x100, 12, 0);
;     __builtin_amdgcn_sched_group_barrier(0x010, 6, 0);
;     __builtin_amdgcn_sched_group_barrier(0x008, 16, 0);
;     asm volatile("s_waitcnt vmcnt(6) lgkmcnt(0)" ::: "memory");
;     __builtin_amdgcn_s_barrier();
;     asm volatile("" ::: "memory");
;     s0 = (s0 == 2 * STG) ? 0 : s0 + STG;
;     s2 = (s2 == 2 * STG) ? 0 : s2 + STG;
;   }
.LBB0_235:
	s_add_i32 s11, s41, 16
	s_mov_b32 s10, s29
	v_add_u32_e32 v142, s11, v219
	v_add_u32_e32 v150, s11, v218
	s_min_u32 s10, s10, 29
	v_add_u32_e32 v142, v142, v220
	v_add_u32_e32 v150, v150, v220
	s_lshl_b32 s70, s10, 6
	ds_read_b128 v[138:141], v142
	ds_read_b128 v[162:165], v150 offset:8192
	ds_read_b128 v[166:169], v150 offset:10240
	ds_read_b128 v[142:145], v142 offset:2048
	ds_read_b128 v[146:149], v150 offset:12288
	ds_read_b128 v[150:153], v150 offset:14336
	s_mul_i32 vcc_lo, s70, 0x12000
	s_add_i32 s10, s13, s40
	v_lshl_add_u64 v[222:223], v[192:193], 0, vcc
	s_mov_b32 m0, s10
	s_mul_i32 s100, s70, 0x900
	v_lshl_add_u64 v[224:225], v[194:195], 0, s[100:101]
	s_add_i32 s10, s28, s40
	s_waitcnt lgkmcnt(6)
	v_mfma_f32_32x32x16_bf16 v[114:129], v[182:185], v[154:157], v[114:129]
	global_load_lds_dwordx4 v[222:223], off
	v_mfma_f32_32x32x16_bf16 v[98:113], v[178:181], v[154:157], v[98:113]
	global_load_lds_dwordx4 v[222:223], off offset:1024
	s_add_i32 m0, s10, 0x2000
	v_mfma_f32_32x32x16_bf16 v[66:81], v[182:185], v[158:161], v[66:81]
	global_load_lds_dwordx4 v[224:225], off
	v_mfma_f32_32x32x16_bf16 v[34:49], v[178:181], v[158:161], v[34:49]
	global_load_lds_dwordx4 v[224:225], off offset:1024
	v_mfma_f32_32x32x16_bf16 v[82:97], v[174:177], v[154:157], v[82:97]
	global_load_lds_dwordx4 v[224:225], off offset:2048
	v_mfma_f32_32x32x16_bf16 v[50:65], v[170:173], v[154:157], v[50:65]
	global_load_lds_dwordx4 v[224:225], off offset:3072
	v_mfma_f32_32x32x16_bf16 v[18:33], v[174:177], v[158:161], v[18:33]
	s_add_i32 s10, s41, 0x6000
	s_cmpk_lg_u32 s41, 0xc000
	s_cselect_b32 s41, s10, 0
	s_add_i32 s10, s40, 0x6000
	s_cmpk_lg_u32 s40, 0xc000
	s_cselect_b32 s40, s10, 0
	v_mfma_f32_32x32x16_bf16 v[2:17], v[170:173], v[158:161], v[2:17]
	s_add_i32 s11, s41, 16
	s_waitcnt vmcnt(6) lgkmcnt(0)
	s_barrier
	v_add_u32_e32 v158, s11, v219
	v_add_u32_e32 v170, s11, v218
	v_add_u32_e32 v158, v158, v0
	v_add_u32_e32 v170, v170, v0
	ds_read_b128 v[154:157], v158
	ds_read_b128 v[182:185], v170 offset:8192
	ds_read_b128 v[178:181], v170 offset:10240
	ds_read_b128 v[158:161], v158 offset:2048
	ds_read_b128 v[174:177], v170 offset:12288
	ds_read_b128 v[170:173], v170 offset:14336
	v_mfma_f32_32x32x16_bf16 v[114:129], v[162:165], v[138:141], v[114:129]
	v_mfma_f32_32x32x16_bf16 v[98:113], v[166:169], v[138:141], v[98:113]
	v_mfma_f32_32x32x16_bf16 v[66:81], v[162:165], v[142:145], v[66:81]
	v_mfma_f32_32x32x16_bf16 v[34:49], v[166:169], v[142:145], v[34:49]
	v_mfma_f32_32x32x16_bf16 v[82:97], v[146:149], v[138:141], v[82:97]
	v_mfma_f32_32x32x16_bf16 v[50:65], v[150:153], v[138:141], v[50:65]
	v_mfma_f32_32x32x16_bf16 v[18:33], v[146:149], v[142:145], v[18:33]
	v_mfma_f32_32x32x16_bf16 v[2:17], v[150:153], v[142:145], v[2:17]
	s_add_i32 s11, s41, 16
	s_add_i32 s10, s29, 1
	v_add_u32_e32 v142, s11, v219
	v_add_u32_e32 v150, s11, v218
	s_min_u32 s10, s10, 29
	v_add_u32_e32 v142, v142, v220
	v_add_u32_e32 v150, v150, v220
	s_lshl_b32 s70, s10, 6
	ds_read_b128 v[138:141], v142
	ds_read_b128 v[162:165], v150 offset:8192
	ds_read_b128 v[166:169], v150 offset:10240
	ds_read_b128 v[142:145], v142 offset:2048
	ds_read_b128 v[146:149], v150 offset:12288
	ds_read_b128 v[150:153], v150 offset:14336
	s_mul_i32 vcc_lo, s70, 0x12000
	s_add_i32 s10, s13, s40
	v_lshl_add_u64 v[222:223], v[192:193], 0, vcc
	s_mov_b32 m0, s10
	s_mul_i32 s100, s70, 0x900
	v_lshl_add_u64 v[224:225], v[194:195], 0, s[100:101]
	s_add_i32 s10, s28, s40
	s_waitcnt lgkmcnt(6)
	v_mfma_f32_32x32x16_bf16 v[114:129], v[182:185], v[154:157], v[114:129]
	global_load_lds_dwordx4 v[222:223], off
	v_mfma_f32_32x32x16_bf16 v[98:113], v[178:181], v[154:157], v[98:113]
	global_load_lds_dwordx4 v[222:223], off offset:1024
	s_add_i32 m0, s10, 0x2000
	v_mfma_f32_32x32x16_bf16 v[66:81], v[182:185], v[158:161], v[66:81]
	global_load_lds_dwordx4 v[224:225], off
	v_mfma_f32_32x32x16_bf16 v[34:49], v[178:181], v[158:161], v[34:49]
	global_load_lds_dwordx4 v[224:225], off offset:1024
	v_mfma_f32_32x32x16_bf16 v[82:97], v[174:177], v[154:157], v[82:97]
	global_load_lds_dwordx4 v[224:225], off offset:2048
	v_mfma_f32_32x32x16_bf16 v[50:65], v[170:173], v[154:157], v[50:65]
	global_load_lds_dwordx4 v[224:225], off offset:3072
	v_mfma_f32_32x32x16_bf16 v[18:33], v[174:177], v[158:161], v[18:33]
	s_add_i32 s10, s41, 0x6000
	s_cmpk_lg_u32 s41, 0xc000
	s_cselect_b32 s41, s10, 0
	s_add_i32 s10, s40, 0x6000
	s_cmpk_lg_u32 s40, 0xc000
	s_cselect_b32 s40, s10, 0
	v_mfma_f32_32x32x16_bf16 v[2:17], v[170:173], v[158:161], v[2:17]
	s_add_i32 s11, s41, 16
	s_waitcnt vmcnt(6) lgkmcnt(0)
	s_barrier
	v_add_u32_e32 v158, s11, v219
	v_add_u32_e32 v170, s11, v218
	v_add_u32_e32 v158, v158, v0
	v_add_u32_e32 v170, v170, v0
	ds_read_b128 v[154:157], v158
	ds_read_b128 v[182:185], v170 offset:8192
	ds_read_b128 v[178:181], v170 offset:10240
	ds_read_b128 v[158:161], v158 offset:2048
	ds_read_b128 v[174:177], v170 offset:12288
	ds_read_b128 v[170:173], v170 offset:14336
	v_mfma_f32_32x32x16_bf16 v[114:129], v[162:165], v[138:141], v[114:129]
	v_mfma_f32_32x32x16_bf16 v[98:113], v[166:169], v[138:141], v[98:113]
	v_mfma_f32_32x32x16_bf16 v[66:81], v[162:165], v[142:145], v[66:81]
	v_mfma_f32_32x32x16_bf16 v[34:49], v[166:169], v[142:145], v[34:49]
	v_mfma_f32_32x32x16_bf16 v[82:97], v[146:149], v[138:141], v[82:97]
	v_mfma_f32_32x32x16_bf16 v[50:65], v[150:153], v[138:141], v[50:65]
	v_mfma_f32_32x32x16_bf16 v[18:33], v[146:149], v[142:145], v[18:33]
	v_mfma_f32_32x32x16_bf16 v[2:17], v[150:153], v[142:145], v[2:17]
	s_add_i32 s29, s29, 2
	s_cmp_lg_u32 s29, 32
	s_cbranch_scc1 .LBB0_235
; DI unsigned pk2(float a, float b) { f32x2 v = {a, b}; bf2_t r = __builtin_convertvector(v, bf2_t); return __builtin_bit_cast(unsigned, r); }
;     ...
;   asm volatile("s_waitcnt vmcnt(0)" ::: "memory");
;   __builtin_amdgcn_s_barrier();
;   asm volatile("" ::: "memory");
;     ...
;   {
;     const int h = lane >> 5, cl = lane & 31;
; #pragma unroll
;     for (int i = 0; i < 2; ++i)
; #pragma unroll
;       for (int j = 0; j < 4; ++j)
; #pragma unroll
;         for (int g = 0; g < 4; ++g) {
;           u32x2 w; w.x = pk2(acc[i][j][4 * g], acc[i][j][4 * g + 1]); w.y = pk2(acc[i][j][4 * g + 2], acc[i][j][4 * g + 3]);
;           *(u32x2*)(smem + (wr * 64 + i * 32 + cl) * 528 + (wc * 128 + j * 32 + 8 * g + 4 * h) * 2) = w;
;         }
;   }
;   __syncthreads();
	s_waitcnt lgkmcnt(0)
	s_setprio 0
	v_mul_lo_u32 v0, v197, s55
	v_add_u32_e32 v0, 16, v0
	s_nop 1
	v_cvt_pk_bf16_f32 v114, v114, v115
	v_cvt_pk_bf16_f32 v115, v116, v117
	v_lshlrev_b32_e32 v116, 3, v196
	s_lshl_b32 s10, s23, 1
	v_add3_u32 v0, v0, v116, s10
	v_cvt_pk_bf16_f32 v116, v118, v119
	v_cvt_pk_bf16_f32 v117, v120, v121
	v_cvt_pk_bf16_f32 v98, v98, v99
	v_cvt_pk_bf16_f32 v99, v100, v101
	v_cvt_pk_bf16_f32 v100, v102, v103
	v_cvt_pk_bf16_f32 v101, v104, v105
	v_cvt_pk_bf16_f32 v82, v82, v83
	v_cvt_pk_bf16_f32 v83, v84, v85
	v_cvt_pk_bf16_f32 v84, v86, v87
	v_cvt_pk_bf16_f32 v85, v88, v89
	v_cvt_pk_bf16_f32 v50, v50, v51
	v_cvt_pk_bf16_f32 v51, v52, v53
	v_cvt_pk_bf16_f32 v52, v54, v55
	v_cvt_pk_bf16_f32 v53, v56, v57
	s_waitcnt vmcnt(0)
	s_barrier
	ds_write2_b64 v0, v[114:115], v[116:117] offset1:2
	v_cvt_pk_bf16_f32 v114, v122, v123
	v_cvt_pk_bf16_f32 v115, v124, v125
	v_cvt_pk_bf16_f32 v116, v126, v127
	v_cvt_pk_bf16_f32 v117, v128, v129
	ds_write2_b64 v0, v[98:99], v[100:101] offset0:8 offset1:10
	v_cvt_pk_bf16_f32 v98, v106, v107
	v_cvt_pk_bf16_f32 v99, v108, v109
	v_cvt_pk_bf16_f32 v100, v110, v111
	v_cvt_pk_bf16_f32 v101, v112, v113
	ds_write2_b64 v0, v[82:83], v[84:85] offset0:16 offset1:18
	v_cvt_pk_bf16_f32 v82, v90, v91
	v_cvt_pk_bf16_f32 v83, v92, v93
	v_cvt_pk_bf16_f32 v84, v94, v95
	v_cvt_pk_bf16_f32 v85, v96, v97
	ds_write2_b64 v0, v[50:51], v[52:53] offset0:24 offset1:26
	v_cvt_pk_bf16_f32 v50, v58, v59
	v_cvt_pk_bf16_f32 v51, v60, v61
	v_cvt_pk_bf16_f32 v52, v62, v63
	v_cvt_pk_bf16_f32 v53, v64, v65
	ds_write2_b64 v0, v[114:115], v[116:117] offset0:4 offset1:6
	ds_write2_b64 v0, v[98:99], v[100:101] offset0:12 offset1:14
	ds_write2_b64 v0, v[82:83], v[84:85] offset0:20 offset1:22
	ds_write2_b64 v0, v[50:51], v[52:53] offset0:28 offset1:30
	v_cvt_pk_bf16_f32 v50, v66, v67
	v_cvt_pk_bf16_f32 v51, v68, v69
	v_cvt_pk_bf16_f32 v52, v70, v71
	v_cvt_pk_bf16_f32 v53, v72, v73
	v_add_u32_e32 v0, 0x4000, v0
	v_cvt_pk_bf16_f32 v34, v34, v35
	v_cvt_pk_bf16_f32 v35, v36, v37
	v_cvt_pk_bf16_f32 v36, v38, v39
	v_cvt_pk_bf16_f32 v37, v40, v41
	v_cvt_pk_bf16_f32 v18, v18, v19
	v_cvt_pk_bf16_f32 v19, v20, v21
	v_cvt_pk_bf16_f32 v20, v22, v23
	v_cvt_pk_bf16_f32 v21, v24, v25
	v_cvt_pk_bf16_f32 v2, v2, v3
	v_cvt_pk_bf16_f32 v3, v4, v5
	v_cvt_pk_bf16_f32 v4, v6, v7
	v_cvt_pk_bf16_f32 v5, v8, v9
	ds_write2_b64 v0, v[50:51], v[52:53] offset0:64 offset1:66
	v_cvt_pk_bf16_f32 v50, v74, v75
	v_cvt_pk_bf16_f32 v51, v76, v77
	v_cvt_pk_bf16_f32 v52, v78, v79
	v_cvt_pk_bf16_f32 v53, v80, v81
	ds_write2_b64 v0, v[34:35], v[36:37] offset0:72 offset1:74
	v_cvt_pk_bf16_f32 v34, v42, v43
	v_cvt_pk_bf16_f32 v35, v44, v45
	v_cvt_pk_bf16_f32 v36, v46, v47
	v_cvt_pk_bf16_f32 v37, v48, v49
	ds_write2_b64 v0, v[18:19], v[20:21] offset0:80 offset1:82
	v_cvt_pk_bf16_f32 v18, v26, v27
	v_cvt_pk_bf16_f32 v19, v28, v29
	v_cvt_pk_bf16_f32 v20, v30, v31
	v_cvt_pk_bf16_f32 v21, v32, v33
	ds_write2_b64 v0, v[2:3], v[4:5] offset0:88 offset1:90
	v_cvt_pk_bf16_f32 v2, v10, v11
	v_cvt_pk_bf16_f32 v3, v12, v13
	v_cvt_pk_bf16_f32 v4, v14, v15
	v_cvt_pk_bf16_f32 v5, v16, v17
	s_lshl_b64 s[10:11], s[14:15], 1
	ds_write2_b64 v0, v[50:51], v[52:53] offset0:68 offset1:70
	ds_write2_b64 v0, v[34:35], v[36:37] offset0:76 offset1:78
	ds_write2_b64 v0, v[18:19], v[20:21] offset0:84 offset1:86
	ds_write2_b64 v0, v[2:3], v[4:5] offset0:92 offset1:94
	s_waitcnt vmcnt(0) lgkmcnt(0)
	s_barrier
; #define GAS __attribute__((address_space(1)))
;     ...
;   int tid2 = tid; asm volatile("" : "+v"(tid2));
;   if (EPI == 0) {
; #pragma unroll
;     for (int i = 0; i < 16; ++i) {
;       const int id = tid2 + 256 * i, r = id >> 5, c8 = (id & 31) * 8;
;       const u32x4 v = *(const u32x4*)(smem + r * 528 + c8 * 2);
;       *(GAS u32x4*)(ea.out + (size_t)(m0 + r) * ea.ldo + n0 + c8) = v;
;     }
	s_add_u32 s10, s16, s10
	v_lshlrev_b32_e32 v0, 4, v189
	v_and_b32_e32 v0, 0x1f0, v0
	s_addc_u32 s11, s17, s11
	v_add_u32_e32 v10, 16, v0
	v_lshl_add_u64 v[12:13], s[10:11], 0, v[0:1]
	v_ashrrev_i32_e32 v0, 5, v189
	v_mad_u64_u32 v[2:3], s[10:11], v0, s55, v[10:11]
	v_add_u32_e32 v0, s12, v0
	v_mad_i64_i32 v[14:15], s[10:11], v0, s35, v[12:13]
	v_add_u32_e32 v0, 0x100, v189
	ds_read_b128 v[2:5], v2
	v_ashrrev_i32_e32 v0, 5, v0
	v_mad_u64_u32 v[6:7], s[10:11], v0, s55, v[10:11]
	ds_read_b128 v[6:9], v6
	v_add_u32_e32 v0, s12, v0
	s_waitcnt lgkmcnt(1)
	global_store_dwordx4 v[14:15], v[2:5], off nt
	s_nop 1
	v_mad_i64_i32 v[2:3], s[10:11], v0, s35, v[12:13]
	v_add_u32_e32 v0, 0x200, v189
	v_ashrrev_i32_e32 v0, 5, v0
	s_waitcnt lgkmcnt(0)
	global_store_dwordx4 v[2:3], v[6:9], off nt
	v_mad_u64_u32 v[2:3], s[10:11], v0, s55, v[10:11]
	v_add_u32_e32 v0, s12, v0
	v_mad_i64_i32 v[14:15], s[10:11], v0, s35, v[12:13]
	v_add_u32_e32 v0, 0x300, v189
	ds_read_b128 v[2:5], v2
	v_ashrrev_i32_e32 v0, 5, v0
	v_mad_u64_u32 v[6:7], s[10:11], v0, s55, v[10:11]
	ds_read_b128 v[6:9], v6
	v_add_u32_e32 v0, s12, v0
	s_waitcnt lgkmcnt(1)
	global_store_dwordx4 v[14:15], v[2:5], off nt
	s_nop 1
	v_mad_i64_i32 v[2:3], s[10:11], v0, s35, v[12:13]
	v_add_u32_e32 v0, 0x400, v189
	v_ashrrev_i32_e32 v0, 5, v0
	s_waitcnt lgkmcnt(0)
	global_store_dwordx4 v[2:3], v[6:9], off nt
	v_mad_u64_u32 v[2:3], s[10:11], v0, s55, v[10:11]
	v_add_u32_e32 v0, s12, v0
	v_mad_i64_i32 v[14:15], s[10:11], v0, s35, v[12:13]
	v_add_u32_e32 v0, 0x500, v189
	ds_read_b128 v[2:5], v2
	v_ashrrev_i32_e32 v0, 5, v0
	v_mad_u64_u32 v[6:7], s[10:11], v0, s55, v[10:11]
	ds_read_b128 v[6:9], v6
	v_add_u32_e32 v0, s12, v0
	s_waitcnt lgkmcnt(1)
	global_store_dwordx4 v[14:15], v[2:5], off nt
	s_nop 1
	v_mad_i64_i32 v[2:3], s[10:11], v0, s35, v[12:13]
	v_add_u32_e32 v0, 0x600, v189
	v_ashrrev_i32_e32 v0, 5, v0
	s_waitcnt lgkmcnt(0)
	global_store_dwordx4 v[2:3], v[6:9], off nt
	v_mad_u64_u32 v[2:3], s[10:11], v0, s55, v[10:11]
	v_add_u32_e32 v0, s12, v0
	v_mad_i64_i32 v[14:15], s[10:11], v0, s35, v[12:13]
	v_add_u32_e32 v0, 0x700, v189
	ds_read_b128 v[2:5], v2
	v_ashrrev_i32_e32 v0, 5, v0
	v_mad_u64_u32 v[6:7], s[10:11], v0, s55, v[10:11]
	ds_read_b128 v[6:9], v6
	v_add_u32_e32 v0, s12, v0
	s_waitcnt lgkmcnt(1)
	global_store_dwordx4 v[14:15], v[2:5], off nt
	s_nop 1
	v_mad_i64_i32 v[2:3], s[10:11], v0, s35, v[12:13]
	v_add_u32_e32 v0, 0x800, v189
	v_ashrrev_i32_e32 v0, 5, v0
	s_waitcnt lgkmcnt(0)
	global_store_dwordx4 v[2:3], v[6:9], off nt
	v_mad_u64_u32 v[2:3], s[10:11], v0, s55, v[10:11]
	v_add_u32_e32 v0, s12, v0
	v_mad_i64_i32 v[14:15], s[10:11], v0, s35, v[12:13]
	v_add_u32_e32 v0, 0x900, v189
	ds_read_b128 v[2:5], v2
	v_ashrrev_i32_e32 v0, 5, v0
	v_mad_u64_u32 v[6:7], s[10:11], v0, s55, v[10:11]
	ds_read_b128 v[6:9], v6
	v_add_u32_e32 v0, s12, v0
	s_waitcnt lgkmcnt(1)
	global_store_dwordx4 v[14:15], v[2:5], off nt
	s_nop 1
	v_mad_i64_i32 v[2:3], s[10:11], v0, s35, v[12:13]
	v_add_u32_e32 v0, 0xa00, v189
	v_ashrrev_i32_e32 v0, 5, v0
	s_waitcnt lgkmcnt(0)
	global_store_dwordx4 v[2:3], v[6:9], off nt
	v_mad_u64_u32 v[2:3], s[10:11], v0, s55, v[10:11]
	v_add_u32_e32 v0, s12, v0
	v_mad_i64_i32 v[14:15], s[10:11], v0, s35, v[12:13]
	v_add_u32_e32 v0, 0xb00, v189
	ds_read_b128 v[2:5], v2
	v_ashrrev_i32_e32 v0, 5, v0
	v_mad_u64_u32 v[6:7], s[10:11], v0, s55, v[10:11]
	ds_read_b128 v[6:9], v6
	v_add_u32_e32 v0, s12, v0
	s_waitcnt lgkmcnt(1)
	global_store_dwordx4 v[14:15], v[2:5], off nt
	s_nop 1
	v_mad_i64_i32 v[2:3], s[10:11], v0, s35, v[12:13]
	v_add_u32_e32 v0, 0xc00, v189
	v_ashrrev_i32_e32 v0, 5, v0
	s_waitcnt lgkmcnt(0)
	global_store_dwordx4 v[2:3], v[6:9], off nt
	v_mad_u64_u32 v[2:3], s[10:11], v0, s55, v[10:11]
	v_add_u32_e32 v0, s12, v0
	v_mad_i64_i32 v[14:15], s[10:11], v0, s35, v[12:13]
	v_add_u32_e32 v0, 0xd00, v189
	ds_read_b128 v[2:5], v2
	v_ashrrev_i32_e32 v0, 5, v0
	v_mad_u64_u32 v[6:7], s[10:11], v0, s55, v[10:11]
	ds_read_b128 v[6:9], v6
	v_add_u32_e32 v0, s12, v0
	s_waitcnt lgkmcnt(1)
	global_store_dwordx4 v[14:15], v[2:5], off nt
	s_nop 1
	v_mad_i64_i32 v[2:3], s[10:11], v0, s35, v[12:13]
	v_add_u32_e32 v0, 0xe00, v189
	v_ashrrev_i32_e32 v0, 5, v0
	s_waitcnt lgkmcnt(0)
	global_store_dwordx4 v[2:3], v[6:9], off nt
	v_mad_u64_u32 v[2:3], s[10:11], v0, s55, v[10:11]
	ds_read_b128 v[2:5], v2
	v_add_u32_e32 v0, s12, v0
	v_mad_i64_i32 v[14:15], s[10:11], v0, s35, v[12:13]
	v_add_u32_e32 v0, 0xf00, v189
	v_ashrrev_i32_e32 v0, 5, v0
	v_mad_u64_u32 v[6:7], s[10:11], v0, s55, v[10:11]
	ds_read_b128 v[6:9], v6
	v_add_u32_e32 v0, s12, v0
	s_waitcnt lgkmcnt(1)
	global_store_dwordx4 v[14:15], v[2:5], off nt
	s_nop 1
	v_mad_i64_i32 v[2:3], s[10:11], v0, s35, v[12:13]
	v_readlane_b32 s10, v252, 12
	s_add_i32 s22, s22, s10
	v_readlane_b32 s10, v252, 38
	s_cmp_ge_i32 s22, s10
	s_waitcnt lgkmcnt(0)
	global_store_dwordx4 v[2:3], v[6:9], off nt
	s_barrier
	s_cbranch_scc0 .LBB0_230

; #define LAS __attribute__((address_space(3)))
; DI f32x16 mfma32(bf16x8 a, bf16x8 b, f32x16 c) { return __builtin_amdgcn_mfma_f32_32x32x16_bf16(a, b, c, 0, 0, 0); }
;     ...
;   for (int kt = 0; kt < nk; ++kt) {
;     const int kn = (kt + 2 < nk) ? (kt + 2) : (nk - 1);
;     const LAS char* cur = lds + s0;
;     bf16x8 af[2][2], bfr[2][4];
; #pragma unroll
;     for (int kk = 0; kk < 2; ++kk) {
;       const int xo = kk ? x1 : x0;
;       af[kk][0] = *(const LAS bf16x8*)(cur + a_rd + xo);
;       bfr[kk][0] = *(const LAS bf16x8*)(cur + b_rd + xo);
;       bfr[kk][1] = *(const LAS bf16x8*)(cur + b_rd + 2048 + xo);
;       af[kk][1] = *(const LAS bf16x8*)(cur + a_rd + 2048 + xo);
;       bfr[kk][2] = *(const LAS bf16x8*)(cur + b_rd + 4096 + xo);
;       bfr[kk][3] = *(const LAS bf16x8*)(cur + b_rd + 6144 + xo);
;     }
;     DMA_STEP_(kn, s2);
; #pragma unroll
;     for (int kk = 0; kk < 2; ++kk) {
;       acc[0][0] = mfma32(bfr[kk][0], af[kk][0], acc[0][0]); acc[0][1] = mfma32(bfr[kk][1], af[kk][0], acc[0][1]);
;       acc[1][0] = mfma32(bfr[kk][0], af[kk][1], acc[1][0]); acc[1][1] = mfma32(bfr[kk][1], af[kk][1], acc[1][1]);
;       acc[0][2] = mfma32(bfr[kk][2], af[kk][0], acc[0][2]); acc[0][3] = mfma32(bfr[kk][3], af[kk][0], acc[0][3]);
;       acc[1][2] = mfma32(bfr[kk][2], af[kk][1], acc[1][2]); acc[1][3] = mfma32(bfr[kk][3], af[kk][1], acc[1][3]);
;     }
;     __builtin_amdgcn_sched_group_barrier(0x100, 12, 0);
;     __builtin_amdgcn_sched_group_barrier(0x010, 6, 0);
;     __builtin_amdgcn_sched_group_barrier(0x008, 16, 0);
;     asm volatile("s_waitcnt vmcnt(6) lgkmcnt(0)" ::: "memory");
;     __builtin_amdgcn_s_barrier();
;     asm volatile("" ::: "memory");
;     s0 = (s0 == 2 * STG) ? 0 : s0 + STG;
;     s2 = (s2 == 2 * STG) ? 0 : s2 + STG;
;   }
.LBB0_244:
	s_add_i32 s11, s46, 16
	s_add_i32 s10, s41, -1
	v_add_u32_e32 v142, s11, v219
	v_add_u32_e32 v150, s11, v218
	s_min_u32 s10, s10, 0x55
	v_add_u32_e32 v142, v142, v220
	v_add_u32_e32 v150, v150, v220
	s_lshl_b32 s70, s10, 6
	ds_read_b128 v[138:141], v142
	ds_read_b128 v[166:169], v150 offset:8192
	ds_read_b128 v[154:157], v150 offset:10240
	ds_read_b128 v[142:145], v142 offset:2048
	ds_read_b128 v[146:149], v150 offset:12288
	ds_read_b128 v[150:153], v150 offset:14336
	v_lshl_add_u64 v[222:223], v[192:193], 0, s[70:71]
	s_add_i32 s10, s44, s45
	v_lshl_add_u64 v[224:225], v[222:223], 0, s[24:25]
	s_mov_b32 m0, s10
	v_lshl_add_u64 v[222:223], v[222:223], 0, s[98:99]
	s_mul_i32 s100, s70, 0x400
	s_waitcnt lgkmcnt(6)
	v_mfma_f32_32x32x16_bf16 v[114:129], v[182:185], v[158:161], v[114:129]
	global_load_lds_dwordx4 v[224:225], off
	s_add_i32 m0, s10, 0x400
	v_mfma_f32_32x32x16_bf16 v[98:113], v[178:181], v[158:161], v[98:113]
	global_load_lds_dwordx4 v[222:223], off
	v_lshl_add_u64 v[224:225], v[194:195], 0, s[100:101]
	s_add_i32 s10, s43, s45
	s_add_i32 m0, s10, 0x2000
	v_mfma_f32_32x32x16_bf16 v[66:81], v[182:185], v[162:165], v[66:81]
	global_load_lds_dwordx4 v[224:225], off
	v_mfma_f32_32x32x16_bf16 v[34:49], v[178:181], v[162:165], v[34:49]
	global_load_lds_dwordx4 v[224:225], off offset:1024
	v_mfma_f32_32x32x16_bf16 v[82:97], v[174:177], v[158:161], v[82:97]
	global_load_lds_dwordx4 v[224:225], off offset:2048
	v_mfma_f32_32x32x16_bf16 v[50:65], v[170:173], v[158:161], v[50:65]
	global_load_lds_dwordx4 v[224:225], off offset:3072
	v_mfma_f32_32x32x16_bf16 v[18:33], v[174:177], v[162:165], v[18:33]
	s_add_i32 s10, s46, 0x6000
	s_cmpk_lg_u32 s46, 0xc000
	s_cselect_b32 s46, s10, 0
	s_add_i32 s10, s45, 0x6000
	s_cmpk_lg_u32 s45, 0xc000
	s_cselect_b32 s45, s10, 0
	v_mfma_f32_32x32x16_bf16 v[2:17], v[170:173], v[162:165], v[2:17]
	s_add_i32 s11, s46, 16
	s_waitcnt vmcnt(6) lgkmcnt(0)
	s_barrier
	v_add_u32_e32 v162, s11, v219
	v_add_u32_e32 v170, s11, v218
	v_add_u32_e32 v162, v162, v0
	v_add_u32_e32 v170, v170, v0
	ds_read_b128 v[158:161], v162
	ds_read_b128 v[182:185], v170 offset:8192
	ds_read_b128 v[178:181], v170 offset:10240
	ds_read_b128 v[162:165], v162 offset:2048
	ds_read_b128 v[174:177], v170 offset:12288
	ds_read_b128 v[170:173], v170 offset:14336
	v_mfma_f32_32x32x16_bf16 v[114:129], v[166:169], v[138:141], v[114:129]
	v_mfma_f32_32x32x16_bf16 v[98:113], v[154:157], v[138:141], v[98:113]
	v_mfma_f32_32x32x16_bf16 v[66:81], v[166:169], v[142:145], v[66:81]
	v_mfma_f32_32x32x16_bf16 v[34:49], v[154:157], v[142:145], v[34:49]
	v_mfma_f32_32x32x16_bf16 v[82:97], v[146:149], v[138:141], v[82:97]
	v_mfma_f32_32x32x16_bf16 v[50:65], v[150:153], v[138:141], v[50:65]
	v_mfma_f32_32x32x16_bf16 v[18:33], v[146:149], v[142:145], v[18:33]
	v_mfma_f32_32x32x16_bf16 v[2:17], v[150:153], v[142:145], v[2:17]
	s_add_i32 s11, s46, 16
	s_mov_b32 s10, s41
	v_add_u32_e32 v142, s11, v219
	v_add_u32_e32 v150, s11, v218
	s_min_u32 s10, s10, 0x55
	v_add_u32_e32 v142, v142, v220
	v_add_u32_e32 v150, v150, v220
	s_lshl_b32 s70, s10, 6
	ds_read_b128 v[138:141], v142
	ds_read_b128 v[166:169], v150 offset:8192
	ds_read_b128 v[154:157], v150 offset:10240
	ds_read_b128 v[142:145], v142 offset:2048
	ds_read_b128 v[146:149], v150 offset:12288
	ds_read_b128 v[150:153], v150 offset:14336
	v_lshl_add_u64 v[222:223], v[192:193], 0, s[70:71]
	s_add_i32 s10, s44, s45
	v_lshl_add_u64 v[224:225], v[222:223], 0, s[24:25]
	s_mov_b32 m0, s10
	v_lshl_add_u64 v[222:223], v[222:223], 0, s[98:99]
	s_mul_i32 s100, s70, 0x400
	s_waitcnt lgkmcnt(6)
	v_mfma_f32_32x32x16_bf16 v[114:129], v[182:185], v[158:161], v[114:129]
	global_load_lds_dwordx4 v[224:225], off
	s_add_i32 m0, s10, 0x400
	v_mfma_f32_32x32x16_bf16 v[98:113], v[178:181], v[158:161], v[98:113]
	global_load_lds_dwordx4 v[222:223], off
	v_lshl_add_u64 v[224:225], v[194:195], 0, s[100:101]
	s_add_i32 s10, s43, s45
	s_add_i32 m0, s10, 0x2000
	v_mfma_f32_32x32x16_bf16 v[66:81], v[182:185], v[162:165], v[66:81]
	global_load_lds_dwordx4 v[224:225], off
	v_mfma_f32_32x32x16_bf16 v[34:49], v[178:181], v[162:165], v[34:49]
	global_load_lds_dwordx4 v[224:225], off offset:1024
	v_mfma_f32_32x32x16_bf16 v[82:97], v[174:177], v[158:161], v[82:97]
	global_load_lds_dwordx4 v[224:225], off offset:2048
	v_mfma_f32_32x32x16_bf16 v[50:65], v[170:173], v[158:161], v[50:65]
	global_load_lds_dwordx4 v[224:225], off offset:3072
	v_mfma_f32_32x32x16_bf16 v[18:33], v[174:177], v[162:165], v[18:33]
	s_add_i32 s10, s46, 0x6000
	s_cmpk_lg_u32 s46, 0xc000
	s_cselect_b32 s46, s10, 0
	s_add_i32 s10, s45, 0x6000
	s_cmpk_lg_u32 s45, 0xc000
	s_cselect_b32 s45, s10, 0
	v_mfma_f32_32x32x16_bf16 v[2:17], v[170:173], v[162:165], v[2:17]
	s_add_i32 s11, s46, 16
	s_waitcnt vmcnt(6) lgkmcnt(0)
	s_barrier
	v_add_u32_e32 v162, s11, v219
	v_add_u32_e32 v170, s11, v218
	v_add_u32_e32 v162, v162, v0
	v_add_u32_e32 v170, v170, v0
	ds_read_b128 v[158:161], v162
	ds_read_b128 v[182:185], v170 offset:8192
	ds_read_b128 v[178:181], v170 offset:10240
	ds_read_b128 v[162:165], v162 offset:2048
	ds_read_b128 v[174:177], v170 offset:12288
	ds_read_b128 v[170:173], v170 offset:14336
	v_mfma_f32_32x32x16_bf16 v[114:129], v[166:169], v[138:141], v[114:129]
	v_mfma_f32_32x32x16_bf16 v[98:113], v[154:157], v[138:141], v[98:113]
	v_mfma_f32_32x32x16_bf16 v[66:81], v[166:169], v[142:145], v[66:81]
	v_mfma_f32_32x32x16_bf16 v[34:49], v[154:157], v[142:145], v[34:49]
	v_mfma_f32_32x32x16_bf16 v[82:97], v[146:149], v[138:141], v[82:97]
	v_mfma_f32_32x32x16_bf16 v[50:65], v[150:153], v[138:141], v[50:65]
	v_mfma_f32_32x32x16_bf16 v[18:33], v[146:149], v[142:145], v[18:33]
	v_mfma_f32_32x32x16_bf16 v[2:17], v[150:153], v[142:145], v[2:17]
	s_add_i32 s41, s41, 2
	s_cmpk_lg_i32 s41, 0x59
	s_cbranch_scc1 .LBB0_244
; DI unsigned pk2(float a, float b) { f32x2 v = {a, b}; bf2_t r = __builtin_convertvector(v, bf2_t); return __builtin_bit_cast(unsigned, r); }
;     ...
;   asm volatile("s_waitcnt vmcnt(0)" ::: "memory");
;   __builtin_amdgcn_s_barrier();
;   asm volatile("" ::: "memory");
;     ...
;   {
;     const int h = lane >> 5, cl = lane & 31;
; #pragma unroll
;     for (int i = 0; i < 2; ++i)
; #pragma unroll
;       for (int j = 0; j < 4; ++j)
; #pragma unroll
;         for (int g = 0; g < 4; ++g) {
;           u32x2 w; w.x = pk2(acc[i][j][4 * g], acc[i][j][4 * g + 1]); w.y = pk2(acc[i][j][4 * g + 2], acc[i][j][4 * g + 3]);
;           *(u32x2*)(smem + (wr * 64 + i * 32 + cl) * 528 + (wc * 128 + j * 32 + 8 * g + 4 * h) * 2) = w;
;         }
;   }
;   __syncthreads();
	s_waitcnt lgkmcnt(0)
	s_setprio 0
	v_mul_lo_u32 v0, v197, s55
	v_add_u32_e32 v0, 16, v0
	s_nop 1
	v_cvt_pk_bf16_f32 v114, v114, v115
	v_cvt_pk_bf16_f32 v115, v116, v117
	v_lshlrev_b32_e32 v116, 3, v196
	s_lshl_b32 s10, s42, 1
	v_add3_u32 v0, v0, v116, s10
	v_cvt_pk_bf16_f32 v116, v118, v119
	v_cvt_pk_bf16_f32 v117, v120, v121
	v_cvt_pk_bf16_f32 v98, v98, v99
	v_cvt_pk_bf16_f32 v99, v100, v101
	v_cvt_pk_bf16_f32 v100, v102, v103
	v_cvt_pk_bf16_f32 v101, v104, v105
	v_cvt_pk_bf16_f32 v82, v82, v83
	v_cvt_pk_bf16_f32 v83, v84, v85
	v_cvt_pk_bf16_f32 v84, v86, v87
	v_cvt_pk_bf16_f32 v85, v88, v89
	v_cvt_pk_bf16_f32 v50, v50, v51
	v_cvt_pk_bf16_f32 v51, v52, v53
	v_cvt_pk_bf16_f32 v52, v54, v55
	v_cvt_pk_bf16_f32 v53, v56, v57
	s_waitcnt vmcnt(0)
	s_barrier
	ds_write2_b64 v0, v[114:115], v[116:117] offset1:2
	v_cvt_pk_bf16_f32 v114, v122, v123
	v_cvt_pk_bf16_f32 v115, v124, v125
	v_cvt_pk_bf16_f32 v116, v126, v127
	v_cvt_pk_bf16_f32 v117, v128, v129
	ds_write2_b64 v0, v[98:99], v[100:101] offset0:8 offset1:10
	v_cvt_pk_bf16_f32 v98, v106, v107
	v_cvt_pk_bf16_f32 v99, v108, v109
	v_cvt_pk_bf16_f32 v100, v110, v111
	v_cvt_pk_bf16_f32 v101, v112, v113
	ds_write2_b64 v0, v[82:83], v[84:85] offset0:16 offset1:18
	v_cvt_pk_bf16_f32 v82, v90, v91
	v_cvt_pk_bf16_f32 v83, v92, v93
	v_cvt_pk_bf16_f32 v84, v94, v95
	v_cvt_pk_bf16_f32 v85, v96, v97
	ds_write2_b64 v0, v[50:51], v[52:53] offset0:24 offset1:26
	v_cvt_pk_bf16_f32 v50, v58, v59
	v_cvt_pk_bf16_f32 v51, v60, v61
	v_cvt_pk_bf16_f32 v52, v62, v63
	v_cvt_pk_bf16_f32 v53, v64, v65
	ds_write2_b64 v0, v[114:115], v[116:117] offset0:4 offset1:6
	ds_write2_b64 v0, v[98:99], v[100:101] offset0:12 offset1:14
	ds_write2_b64 v0, v[82:83], v[84:85] offset0:20 offset1:22
	ds_write2_b64 v0, v[50:51], v[52:53] offset0:28 offset1:30
	v_cvt_pk_bf16_f32 v50, v66, v67
	v_cvt_pk_bf16_f32 v51, v68, v69
	v_cvt_pk_bf16_f32 v52, v70, v71
	v_cvt_pk_bf16_f32 v53, v72, v73
	v_add_u32_e32 v0, 0x4000, v0
	v_cvt_pk_bf16_f32 v34, v34, v35
	v_cvt_pk_bf16_f32 v35, v36, v37
	v_cvt_pk_bf16_f32 v36, v38, v39
	v_cvt_pk_bf16_f32 v37, v40, v41
	v_cvt_pk_bf16_f32 v18, v18, v19
	v_cvt_pk_bf16_f32 v19, v20, v21
	v_cvt_pk_bf16_f32 v20, v22, v23
	v_cvt_pk_bf16_f32 v21, v24, v25
	v_cvt_pk_bf16_f32 v2, v2, v3
	v_cvt_pk_bf16_f32 v3, v4, v5
	v_cvt_pk_bf16_f32 v4, v6, v7
	v_cvt_pk_bf16_f32 v5, v8, v9
	ds_write2_b64 v0, v[50:51], v[52:53] offset0:64 offset1:66
	v_cvt_pk_bf16_f32 v50, v74, v75
	v_cvt_pk_bf16_f32 v51, v76, v77
	v_cvt_pk_bf16_f32 v52, v78, v79
	v_cvt_pk_bf16_f32 v53, v80, v81
	ds_write2_b64 v0, v[34:35], v[36:37] offset0:72 offset1:74
	v_cvt_pk_bf16_f32 v34, v42, v43
	v_cvt_pk_bf16_f32 v35, v44, v45
	v_cvt_pk_bf16_f32 v36, v46, v47
	v_cvt_pk_bf16_f32 v37, v48, v49
	ds_write2_b64 v0, v[18:19], v[20:21] offset0:80 offset1:82
	v_cvt_pk_bf16_f32 v18, v26, v27
	v_cvt_pk_bf16_f32 v19, v28, v29
	v_cvt_pk_bf16_f32 v20, v30, v31
	v_cvt_pk_bf16_f32 v21, v32, v33
	ds_write2_b64 v0, v[2:3], v[4:5] offset0:88 offset1:90
	v_cvt_pk_bf16_f32 v2, v10, v11
	v_cvt_pk_bf16_f32 v3, v12, v13
	v_cvt_pk_bf16_f32 v4, v14, v15
	v_cvt_pk_bf16_f32 v5, v16, v17
	s_lshl_b64 s[10:11], s[16:17], 1
	ds_write2_b64 v0, v[50:51], v[52:53] offset0:68 offset1:70
	ds_write2_b64 v0, v[34:35], v[36:37] offset0:76 offset1:78
	ds_write2_b64 v0, v[18:19], v[20:21] offset0:84 offset1:86
	ds_write2_b64 v0, v[2:3], v[4:5] offset0:92 offset1:94
	s_waitcnt vmcnt(0) lgkmcnt(0)
	s_barrier
; #define GAS __attribute__((address_space(1)))
;     ...
;   int tid2 = tid; asm volatile("" : "+v"(tid2));
;   if (EPI == 0) {
; #pragma unroll
;     for (int i = 0; i < 16; ++i) {
;       const int id = tid2 + 256 * i, r = id >> 5, c8 = (id & 31) * 8;
;       const u32x4 v = *(const u32x4*)(smem + r * 528 + c8 * 2);
;       *(GAS u32x4*)(ea.out + (size_t)(m0 + r) * ea.ldo + n0 + c8) = v;
;     }
	s_add_u32 s10, s21, s10
	v_lshlrev_b32_e32 v0, 4, v189
	v_and_b32_e32 v0, 0x1f0, v0
	s_addc_u32 s11, s22, s11
	v_add_u32_e32 v10, 16, v0
	v_lshl_add_u64 v[12:13], s[10:11], 0, v[0:1]
	v_ashrrev_i32_e32 v0, 5, v189
	v_mad_u64_u32 v[2:3], s[10:11], v0, s55, v[10:11]
	ds_read_b128 v[2:5], v2
	v_add_u32_e32 v6, s40, v0
	v_ashrrev_i32_e32 v7, 31, v6
	v_add_u32_e32 v0, 0x100, v189
	v_lshlrev_b64 v[6:7], 11, v[6:7]
	v_ashrrev_i32_e32 v0, 5, v0
	v_lshl_add_u64 v[14:15], v[12:13], 0, v[6:7]
	v_mad_u64_u32 v[6:7], s[10:11], v0, s55, v[10:11]
	ds_read_b128 v[6:9], v6
	s_waitcnt lgkmcnt(1)
	global_store_dwordx4 v[14:15], v[2:5], off nt
	s_nop 1
	v_add_u32_e32 v2, s40, v0
	v_ashrrev_i32_e32 v3, 31, v2
	v_lshlrev_b64 v[2:3], 11, v[2:3]
	v_add_u32_e32 v0, 0x200, v189
	v_lshl_add_u64 v[2:3], v[12:13], 0, v[2:3]
	v_ashrrev_i32_e32 v0, 5, v0
	s_waitcnt lgkmcnt(0)
	global_store_dwordx4 v[2:3], v[6:9], off nt
	v_mad_u64_u32 v[2:3], s[10:11], v0, s55, v[10:11]
	ds_read_b128 v[2:5], v2
	v_add_u32_e32 v6, s40, v0
	v_ashrrev_i32_e32 v7, 31, v6
	v_add_u32_e32 v0, 0x300, v189
	v_lshlrev_b64 v[6:7], 11, v[6:7]
	v_ashrrev_i32_e32 v0, 5, v0
	v_lshl_add_u64 v[14:15], v[12:13], 0, v[6:7]
	v_mad_u64_u32 v[6:7], s[10:11], v0, s55, v[10:11]
	ds_read_b128 v[6:9], v6
	s_waitcnt lgkmcnt(1)
	global_store_dwordx4 v[14:15], v[2:5], off nt
	s_nop 1
	v_add_u32_e32 v2, s40, v0
	v_ashrrev_i32_e32 v3, 31, v2
	v_lshlrev_b64 v[2:3], 11, v[2:3]
	v_add_u32_e32 v0, 0x400, v189
	v_lshl_add_u64 v[2:3], v[12:13], 0, v[2:3]
	v_ashrrev_i32_e32 v0, 5, v0
	s_waitcnt lgkmcnt(0)
	global_store_dwordx4 v[2:3], v[6:9], off nt
	v_mad_u64_u32 v[2:3], s[10:11], v0, s55, v[10:11]
	ds_read_b128 v[2:5], v2
	v_add_u32_e32 v6, s40, v0
	v_ashrrev_i32_e32 v7, 31, v6
	v_add_u32_e32 v0, 0x500, v189
	v_lshlrev_b64 v[6:7], 11, v[6:7]
	v_ashrrev_i32_e32 v0, 5, v0
	v_lshl_add_u64 v[14:15], v[12:13], 0, v[6:7]
	v_mad_u64_u32 v[6:7], s[10:11], v0, s55, v[10:11]
	ds_read_b128 v[6:9], v6
	s_waitcnt lgkmcnt(1)
	global_store_dwordx4 v[14:15], v[2:5], off nt
	s_nop 1
	v_add_u32_e32 v2, s40, v0
	v_ashrrev_i32_e32 v3, 31, v2
	v_lshlrev_b64 v[2:3], 11, v[2:3]
	v_add_u32_e32 v0, 0x600, v189
	v_lshl_add_u64 v[2:3], v[12:13], 0, v[2:3]
	v_ashrrev_i32_e32 v0, 5, v0
	s_waitcnt lgkmcnt(0)
	global_store_dwordx4 v[2:3], v[6:9], off nt
	v_mad_u64_u32 v[2:3], s[10:11], v0, s55, v[10:11]
	ds_read_b128 v[2:5], v2
	v_add_u32_e32 v6, s40, v0
	v_ashrrev_i32_e32 v7, 31, v6
	v_add_u32_e32 v0, 0x700, v189
	v_lshlrev_b64 v[6:7], 11, v[6:7]
	v_ashrrev_i32_e32 v0, 5, v0
	v_lshl_add_u64 v[14:15], v[12:13], 0, v[6:7]
	v_mad_u64_u32 v[6:7], s[10:11], v0, s55, v[10:11]
	ds_read_b128 v[6:9], v6
	s_waitcnt lgkmcnt(1)
	global_store_dwordx4 v[14:15], v[2:5], off nt
	s_nop 1
	v_add_u32_e32 v2, s40, v0
	v_ashrrev_i32_e32 v3, 31, v2
	v_lshlrev_b64 v[2:3], 11, v[2:3]
	v_add_u32_e32 v0, 0x800, v189
	v_lshl_add_u64 v[2:3], v[12:13], 0, v[2:3]
	v_ashrrev_i32_e32 v0, 5, v0
	s_waitcnt lgkmcnt(0)
	global_store_dwordx4 v[2:3], v[6:9], off nt
	v_mad_u64_u32 v[2:3], s[10:11], v0, s55, v[10:11]
	ds_read_b128 v[2:5], v2
	v_add_u32_e32 v6, s40, v0
	v_ashrrev_i32_e32 v7, 31, v6
	v_add_u32_e32 v0, 0x900, v189
	v_lshlrev_b64 v[6:7], 11, v[6:7]
	v_ashrrev_i32_e32 v0, 5, v0
	v_lshl_add_u64 v[14:15], v[12:13], 0, v[6:7]
	v_mad_u64_u32 v[6:7], s[10:11], v0, s55, v[10:11]
	ds_read_b128 v[6:9], v6
	s_waitcnt lgkmcnt(1)
	global_store_dwordx4 v[14:15], v[2:5], off nt
	s_nop 1
	v_add_u32_e32 v2, s40, v0
	v_ashrrev_i32_e32 v3, 31, v2
	v_lshlrev_b64 v[2:3], 11, v[2:3]
	v_add_u32_e32 v0, 0xa00, v189
	v_lshl_add_u64 v[2:3], v[12:13], 0, v[2:3]
	v_ashrrev_i32_e32 v0, 5, v0
	s_waitcnt lgkmcnt(0)
	global_store_dwordx4 v[2:3], v[6:9], off nt
	v_mad_u64_u32 v[2:3], s[10:11], v0, s55, v[10:11]
	ds_read_b128 v[2:5], v2
	v_add_u32_e32 v6, s40, v0
	v_ashrrev_i32_e32 v7, 31, v6
	v_add_u32_e32 v0, 0xb00, v189
	v_lshlrev_b64 v[6:7], 11, v[6:7]
	v_ashrrev_i32_e32 v0, 5, v0
	v_lshl_add_u64 v[14:15], v[12:13], 0, v[6:7]
	v_mad_u64_u32 v[6:7], s[10:11], v0, s55, v[10:11]
	ds_read_b128 v[6:9], v6
	s_waitcnt lgkmcnt(1)
	global_store_dwordx4 v[14:15], v[2:5], off nt
	s_nop 1
	v_add_u32_e32 v2, s40, v0
	v_ashrrev_i32_e32 v3, 31, v2
	v_lshlrev_b64 v[2:3], 11, v[2:3]
	v_add_u32_e32 v0, 0xc00, v189
	v_lshl_add_u64 v[2:3], v[12:13], 0, v[2:3]
	v_ashrrev_i32_e32 v0, 5, v0
	s_waitcnt lgkmcnt(0)
	global_store_dwordx4 v[2:3], v[6:9], off nt
	v_mad_u64_u32 v[2:3], s[10:11], v0, s55, v[10:11]
	ds_read_b128 v[2:5], v2
	v_add_u32_e32 v6, s40, v0
	v_ashrrev_i32_e32 v7, 31, v6
	v_add_u32_e32 v0, 0xd00, v189
	v_lshlrev_b64 v[6:7], 11, v[6:7]
	v_ashrrev_i32_e32 v0, 5, v0
	v_lshl_add_u64 v[14:15], v[12:13], 0, v[6:7]
	v_mad_u64_u32 v[6:7], s[10:11], v0, s55, v[10:11]
	ds_read_b128 v[6:9], v6
	s_waitcnt lgkmcnt(1)
	global_store_dwordx4 v[14:15], v[2:5], off nt
	s_nop 1
	v_add_u32_e32 v2, s40, v0
	v_ashrrev_i32_e32 v3, 31, v2
	v_lshlrev_b64 v[2:3], 11, v[2:3]
	v_add_u32_e32 v0, 0xe00, v189
	v_lshl_add_u64 v[2:3], v[12:13], 0, v[2:3]
	v_ashrrev_i32_e32 v0, 5, v0
	s_waitcnt lgkmcnt(0)
	global_store_dwordx4 v[2:3], v[6:9], off nt
	v_mad_u64_u32 v[2:3], s[10:11], v0, s55, v[10:11]
	ds_read_b128 v[2:5], v2
	v_add_u32_e32 v6, s40, v0
	v_ashrrev_i32_e32 v7, 31, v6
	v_add_u32_e32 v0, 0xf00, v189
	v_lshlrev_b64 v[6:7], 11, v[6:7]
	v_ashrrev_i32_e32 v0, 5, v0
	v_lshl_add_u64 v[14:15], v[12:13], 0, v[6:7]
	v_mad_u64_u32 v[6:7], s[10:11], v0, s55, v[10:11]
	ds_read_b128 v[6:9], v6
	s_waitcnt lgkmcnt(1)
	global_store_dwordx4 v[14:15], v[2:5], off nt
	v_readlane_b32 s10, v252, 12
	s_add_i32 s29, s29, s10
	v_add_u32_e32 v2, s40, v0
	v_ashrrev_i32_e32 v3, 31, v2
	v_lshlrev_b64 v[2:3], 11, v[2:3]
	v_lshl_add_u64 v[2:3], v[12:13], 0, v[2:3]
	s_cmp_ge_i32 s29, s18
	s_waitcnt lgkmcnt(0)
	global_store_dwordx4 v[2:3], v[6:9], off nt
	s_barrier
	s_cbranch_scc0 .LBB0_243
